# GEMM K-loops: 8 of 16 LDS-DMA loads per iteration use the saddr form (SGPR base + 32-bit lane offset), removing the 64-bit VALU adds from the load segments that run beside the partner's MFMA block
# speedup vs baseline: 1.0047x; 1.0013x over previous
; #define PG8_STAGE(bufoff, gbase, voff) do { _Pragma("unroll") for (int _i = 0; _i < 2; ++_i) \
;         __builtin_amdgcn_global_load_lds((const unsigned*)((const char*)(gbase) + (voff)[_i]), (PG8_LAS unsigned*)(lds + (bufoff) + ldsw + _i * 8192), 16, 0, 0); } while (0)
; #define PG8_LDA(dst, b, h) do { _Pragma("unroll") for (int m = 0; m < 4; ++m) _Pragma("unroll") for (int k = 0; k < 2; ++k) dst[m][k] = *(const PG8_LAS bf16x8*)(lds + PG8_SA(b, h) + aoff + m * 2048 + k * 1024); } while (0)
; #define PG8_LDB(dst, b, h) do { _Pragma("unroll") for (int n = 0; n < 2; ++n) _Pragma("unroll") for (int k = 0; k < 2; ++k) dst[n][k] = *(const PG8_LAS bf16x8*)(lds + PG8_SB(b, h) + boff + n * 2048 + k * 1024); } while (0)
; #define PG8_MMA(ai, bj, At, Bt) do { __builtin_amdgcn_s_setprio(1); _Pragma("unroll") for (int m = 0; m < 4; ++m) _Pragma("unroll") for (int n = 0; n < 2; ++n) _Pragma("unroll") for (int k = 0; k < 2; ++k) \
;         acc[ai][bj][m][n] = __builtin_amdgcn_mfma_f32_16x16x32_bf16(Bt[n][k], At[m][k], acc[ai][bj][m][n], 0, 0, 0); __builtin_amdgcn_s_setprio(0); } while (0)
; #define PG8_WAIT_V(n) asm volatile("s_waitcnt vmcnt(" #n ")" ::: "memory")
; #define PG8_WAIT_L(n) asm volatile("s_waitcnt lgkmcnt(" #n ")" ::: "memory")
; template <class Epi, class Sched, bool ALIGN_EPI = false, bool SP2 = false>
; __device__ __forceinline__ void gemm_phase(PG8_LAS unsigned char* lds, const Gemm g, const Sched& S, const Epi& E) {
;     ...
;             const bool last = (t == nt - 2);
;             const char* a1 = cA + (size_t)(t + 1) * kstep;
;             const char* a2 = last ? nA : cA + (size_t)(t + 2) * kstep; const char* b2 = last ? nB : cB + (size_t)(t + 2) * kstep;
;             const char* a3 = a2 + kstep; const char* b3 = b2 + kstep;
;             if (last && has_next) S.a_ready(nxt);
;             if constexpr (SP2) {
;             PG8_LDB(B0, 0, 0); PG8_LDB(B1, 0, 1); PG8_SCHED; PG8_LDA(At, 0, 0); PG8_STAGE(PG8_SA(1, 1), a1 + hstep, voffA);
;             PG8_WAIT_V(8); PG8_WAIT_L(0); PG8_BAR; PG8_MMA(0, 0, At, B0); PG8_MMA(0, 1, At, B1); PG8_BAR; PG8_SCHED;
;             PG8_LDA(At, 0, 1); PG8_STAGE(PG8_SB(0, 0), b2, voffB); PG8_STAGE(PG8_SB(0, 1), b2 + hstep, voffB); PG8_STAGE(PG8_SA(0, 0), a2, voffA);
;             PG8_WAIT_V(8); PG8_WAIT_L(0); PG8_BAR; PG8_MMA(1, 0, At, B0); PG8_MMA(1, 1, At, B1); PG8_BAR; PG8_SCHED;
.LBB0_111:
	s_add_u32 s76, s12, 0xfffc0080
	s_addc_u32 s77, s13, -1
	s_add_i32 s80, 0, 0x10000
	s_cmp_eq_u32 s69, 12
	s_cselect_b32 s79, s11, s77
	s_cselect_b32 s78, s22, s76
	s_cselect_b32 s77, s23, s67
	s_cselect_b32 s76, s40, s41
	s_add_i32 s86, 0, 0x14000
	v_add_u32_e32 v146, s80, v159
	v_add_u32_e32 v182, s86, v159
	ds_read_b128 v[134:137], v146
	ds_read_b128 v[138:141], v146 offset:1024
	ds_read_b128 v[142:145], v146 offset:2048
	ds_read_b128 v[146:149], v146 offset:3072
	ds_read_b128 v[166:169], v182
	ds_read_b128 v[170:173], v182 offset:1024
	ds_read_b128 v[174:177], v182 offset:2048
	ds_read_b128 v[182:185], v182 offset:3072
	s_add_i32 m0, s37, 0xc000
	ds_read_b128 v[200:203], v180
	ds_read_b128 v[204:207], v180 offset:1024
	ds_read_b128 v[208:211], v180 offset:2048
	ds_read_b128 v[212:215], v180 offset:3072
	ds_read_b128 v[216:219], v180 offset:4096
	ds_read_b128 v[220:223], v180 offset:5120
	ds_read_b128 v[224:227], v180 offset:6144
	ds_read_b128 v[228:231], v180 offset:7168
	global_load_lds_dwordx4 v164, s[12:13]
	s_add_i32 m0, s37, 0xe000
	s_nop 0
	global_load_lds_dwordx4 v162, s[12:13]
	s_waitcnt vmcnt(8)
	s_waitcnt lgkmcnt(0)
	s_barrier
	s_setprio 1
	v_mfma_f32_16x16x32_bf16 v[130:133], v[134:137], v[200:203], v[130:133]
	v_mfma_f32_16x16x32_bf16 v[126:129], v[142:145], v[200:203], v[126:129]
	v_mfma_f32_16x16x32_bf16 v[114:117], v[134:137], v[208:211], v[114:117]
	v_mfma_f32_16x16x32_bf16 v[110:113], v[142:145], v[208:211], v[110:113]
	v_mfma_f32_16x16x32_bf16 v[98:101], v[134:137], v[216:219], v[98:101]
	v_mfma_f32_16x16x32_bf16 v[94:97], v[142:145], v[216:219], v[94:97]
	v_mfma_f32_16x16x32_bf16 v[78:81], v[134:137], v[224:227], v[78:81]
	v_mfma_f32_16x16x32_bf16 v[74:77], v[142:145], v[224:227], v[74:77]
	v_mfma_f32_16x16x32_bf16 v[130:133], v[138:141], v[204:207], v[130:133]
	v_mfma_f32_16x16x32_bf16 v[126:129], v[146:149], v[204:207], v[126:129]
	v_mfma_f32_16x16x32_bf16 v[114:117], v[138:141], v[212:215], v[114:117]
	v_mfma_f32_16x16x32_bf16 v[110:113], v[146:149], v[212:215], v[110:113]
	v_mfma_f32_16x16x32_bf16 v[98:101], v[138:141], v[220:223], v[98:101]
	v_mfma_f32_16x16x32_bf16 v[94:97], v[146:149], v[220:223], v[94:97]
	v_mfma_f32_16x16x32_bf16 v[78:81], v[138:141], v[228:231], v[78:81]
	v_mfma_f32_16x16x32_bf16 v[74:77], v[146:149], v[228:231], v[74:77]
	v_mfma_f32_16x16x32_bf16 v[122:125], v[166:169], v[200:203], v[122:125]
	v_mfma_f32_16x16x32_bf16 v[118:121], v[174:177], v[200:203], v[118:121]
	v_mfma_f32_16x16x32_bf16 v[106:109], v[166:169], v[208:211], v[106:109]
	v_mfma_f32_16x16x32_bf16 v[102:105], v[174:177], v[208:211], v[102:105]
	v_mfma_f32_16x16x32_bf16 v[90:93], v[166:169], v[216:219], v[90:93]
	v_mfma_f32_16x16x32_bf16 v[86:89], v[174:177], v[216:219], v[86:89]
	v_mfma_f32_16x16x32_bf16 v[70:73], v[166:169], v[224:227], v[70:73]
	v_mfma_f32_16x16x32_bf16 v[66:69], v[174:177], v[224:227], v[66:69]
	v_mfma_f32_16x16x32_bf16 v[122:125], v[170:173], v[204:207], v[122:125]
	v_mfma_f32_16x16x32_bf16 v[118:121], v[182:185], v[204:207], v[118:121]
	v_mfma_f32_16x16x32_bf16 v[106:109], v[170:173], v[212:215], v[106:109]
	v_mfma_f32_16x16x32_bf16 v[102:105], v[182:185], v[212:215], v[102:105]
	v_mfma_f32_16x16x32_bf16 v[90:93], v[170:173], v[220:223], v[90:93]
	v_mfma_f32_16x16x32_bf16 v[86:89], v[182:185], v[220:223], v[86:89]
	v_mfma_f32_16x16x32_bf16 v[70:73], v[170:173], v[228:231], v[70:73]
	v_mfma_f32_16x16x32_bf16 v[66:69], v[182:185], v[228:231], v[66:69]
	s_setprio 0
	s_barrier
	s_add_i32 s80, s80, s36
	v_lshl_add_u64 v[186:187], s[76:77], 0, v[152:153]
	s_mov_b32 m0, s80
	ds_read_b128 v[200:203], v180 offset:16384
	ds_read_b128 v[204:207], v180 offset:17408
	ds_read_b128 v[208:211], v180 offset:18432
	ds_read_b128 v[212:215], v180 offset:19456
	ds_read_b128 v[216:219], v180 offset:20480
	ds_read_b128 v[220:223], v180 offset:21504
	ds_read_b128 v[224:227], v180 offset:22528
	ds_read_b128 v[228:231], v180 offset:23552
	global_load_lds_dwordx4 v[186:187], off
	s_add_i32 m0, s80, 0x2000
	s_add_u32 s80, s76, 0x40000
	v_lshl_add_u64 v[232:233], s[76:77], 0, v[156:157]
	s_addc_u32 s81, s77, 0
	s_add_i32 s86, s86, s36
	global_load_lds_dwordx4 v[232:233], off
	s_mov_b32 m0, s86
	v_lshl_add_u64 v[236:237], s[78:79], 0, v[154:155]
	global_load_lds_dwordx4 v152, s[80:81]
	s_add_i32 m0, s86, 0x2000
	s_nop 0
	global_load_lds_dwordx4 v156, s[80:81]
	v_lshl_add_u64 v[234:235], s[78:79], 0, v[150:151]
	s_mov_b32 m0, s37
	s_nop 0
	global_load_lds_dwordx4 v[234:235], off
	s_mov_b32 m0, s42
	s_nop 0
	global_load_lds_dwordx4 v[236:237], off
	s_waitcnt vmcnt(8)
	s_waitcnt lgkmcnt(0)
	s_barrier
; #define PG8_STAGE(bufoff, gbase, voff) do { _Pragma("unroll") for (int _i = 0; _i < 2; ++_i) \
;         __builtin_amdgcn_global_load_lds((const unsigned*)((const char*)(gbase) + (voff)[_i]), (PG8_LAS unsigned*)(lds + (bufoff) + ldsw + _i * 8192), 16, 0, 0); } while (0)
; #define PG8_LDA(dst, b, h) do { _Pragma("unroll") for (int m = 0; m < 4; ++m) _Pragma("unroll") for (int k = 0; k < 2; ++k) dst[m][k] = *(const PG8_LAS bf16x8*)(lds + PG8_SA(b, h) + aoff + m * 2048 + k * 1024); } while (0)
; #define PG8_LDB(dst, b, h) do { _Pragma("unroll") for (int n = 0; n < 2; ++n) _Pragma("unroll") for (int k = 0; k < 2; ++k) dst[n][k] = *(const PG8_LAS bf16x8*)(lds + PG8_SB(b, h) + boff + n * 2048 + k * 1024); } while (0)
; #define PG8_MMA(ai, bj, At, Bt) do { __builtin_amdgcn_s_setprio(1); _Pragma("unroll") for (int m = 0; m < 4; ++m) _Pragma("unroll") for (int n = 0; n < 2; ++n) _Pragma("unroll") for (int k = 0; k < 2; ++k) \
;         acc[ai][bj][m][n] = __builtin_amdgcn_mfma_f32_16x16x32_bf16(Bt[n][k], At[m][k], acc[ai][bj][m][n], 0, 0, 0); __builtin_amdgcn_s_setprio(0); } while (0)
; #define PG8_WAIT_V(n) asm volatile("s_waitcnt vmcnt(" #n ")" ::: "memory")
; #define PG8_WAIT_L(n) asm volatile("s_waitcnt lgkmcnt(" #n ")" ::: "memory")
; #define PG8_BAR __builtin_amdgcn_s_barrier()
; #define PG8_SCHED __builtin_amdgcn_sched_barrier(0)
; template <class Epi, class Sched, bool ALIGN_EPI = false, bool SP2 = false>
; __device__ __forceinline__ void gemm_phase(PG8_LAS unsigned char* lds, const Gemm g, const Sched& S, const Epi& E) {
;     ...
;             PG8_WAIT_V(8); PG8_WAIT_L(0); PG8_BAR; PG8_MMA(1, 0, At, B0); PG8_MMA(1, 1, At, B1); PG8_BAR; PG8_SCHED;
;             PG8_LDB(B0, 1, 0); PG8_LDB(B1, 1, 1); PG8_SCHED; PG8_LDA(At, 1, 0); PG8_STAGE(PG8_SA(0, 1), a2 + hstep, voffA);
;             PG8_WAIT_V(8); PG8_WAIT_L(0); PG8_BAR; PG8_MMA(0, 0, At, B0); PG8_MMA(0, 1, At, B1); PG8_BAR; PG8_SCHED;
	s_setprio 1
	v_mfma_f32_16x16x32_bf16 v[62:65], v[134:137], v[200:203], v[62:65]
	v_mfma_f32_16x16x32_bf16 v[58:61], v[142:145], v[200:203], v[58:61]
	v_mfma_f32_16x16x32_bf16 v[46:49], v[134:137], v[208:211], v[46:49]
	v_mfma_f32_16x16x32_bf16 v[42:45], v[142:145], v[208:211], v[42:45]
	v_mfma_f32_16x16x32_bf16 v[30:33], v[134:137], v[216:219], v[30:33]
	v_mfma_f32_16x16x32_bf16 v[26:29], v[142:145], v[216:219], v[26:29]
	v_mfma_f32_16x16x32_bf16 v[14:17], v[134:137], v[224:227], v[14:17]
	v_mfma_f32_16x16x32_bf16 v[10:13], v[142:145], v[224:227], v[10:13]
	v_mfma_f32_16x16x32_bf16 v[62:65], v[138:141], v[204:207], v[62:65]
	v_mfma_f32_16x16x32_bf16 v[58:61], v[146:149], v[204:207], v[58:61]
	v_mfma_f32_16x16x32_bf16 v[46:49], v[138:141], v[212:215], v[46:49]
	v_mfma_f32_16x16x32_bf16 v[42:45], v[146:149], v[212:215], v[42:45]
	v_mfma_f32_16x16x32_bf16 v[30:33], v[138:141], v[220:223], v[30:33]
	v_mfma_f32_16x16x32_bf16 v[26:29], v[146:149], v[220:223], v[26:29]
	v_mfma_f32_16x16x32_bf16 v[14:17], v[138:141], v[228:231], v[14:17]
	v_mfma_f32_16x16x32_bf16 v[10:13], v[146:149], v[228:231], v[10:13]
	v_mfma_f32_16x16x32_bf16 v[54:57], v[166:169], v[200:203], v[54:57]
	v_mfma_f32_16x16x32_bf16 v[50:53], v[174:177], v[200:203], v[50:53]
	v_mfma_f32_16x16x32_bf16 v[38:41], v[166:169], v[208:211], v[38:41]
	v_mfma_f32_16x16x32_bf16 v[34:37], v[174:177], v[208:211], v[34:37]
	v_mfma_f32_16x16x32_bf16 v[22:25], v[166:169], v[216:219], v[22:25]
	v_mfma_f32_16x16x32_bf16 v[18:21], v[174:177], v[216:219], v[18:21]
	v_mfma_f32_16x16x32_bf16 v[6:9], v[166:169], v[224:227], v[6:9]
	v_mfma_f32_16x16x32_bf16 v[2:5], v[174:177], v[224:227], v[2:5]
	v_mfma_f32_16x16x32_bf16 v[54:57], v[170:173], v[204:207], v[54:57]
	v_mfma_f32_16x16x32_bf16 v[50:53], v[182:185], v[204:207], v[50:53]
	v_mfma_f32_16x16x32_bf16 v[38:41], v[170:173], v[212:215], v[38:41]
	v_mfma_f32_16x16x32_bf16 v[34:37], v[182:185], v[212:215], v[34:37]
	v_mfma_f32_16x16x32_bf16 v[22:25], v[170:173], v[220:223], v[22:25]
	v_mfma_f32_16x16x32_bf16 v[18:21], v[182:185], v[220:223], v[18:21]
	v_mfma_f32_16x16x32_bf16 v[6:9], v[170:173], v[228:231], v[6:9]
	v_mfma_f32_16x16x32_bf16 v[2:5], v[182:185], v[228:231], v[2:5]
	s_setprio 0
	s_barrier
	s_add_i32 s80, 0, 0x18000
	s_add_i32 s81, 0, 0x1c000
	v_add_u32_e32 v146, s80, v159
	v_add_u32_e32 v182, s81, v159
	ds_read_b128 v[134:137], v146
	ds_read_b128 v[138:141], v146 offset:1024
	ds_read_b128 v[142:145], v146 offset:2048
	ds_read_b128 v[146:149], v146 offset:3072
	ds_read_b128 v[166:169], v182
	ds_read_b128 v[170:173], v182 offset:1024
	ds_read_b128 v[174:177], v182 offset:2048
	ds_read_b128 v[182:185], v182 offset:3072
	s_add_u32 s78, s78, 0x40000
	s_addc_u32 s79, s79, 0
	s_mov_b32 m0, s48
	ds_read_b128 v[200:203], v180 offset:32768
	ds_read_b128 v[204:207], v180 offset:33792
	ds_read_b128 v[208:211], v180 offset:34816
	ds_read_b128 v[212:215], v180 offset:35840
	ds_read_b128 v[216:219], v180 offset:36864
	ds_read_b128 v[220:223], v180 offset:37888
	ds_read_b128 v[224:227], v180 offset:38912
	ds_read_b128 v[228:231], v180 offset:39936
	global_load_lds_dwordx4 v150, s[78:79]
	s_mov_b32 m0, s49
	s_nop 0
	global_load_lds_dwordx4 v154, s[78:79]
	s_waitcnt vmcnt(8)
	s_waitcnt lgkmcnt(0)
	s_barrier
	s_setprio 1
	v_mfma_f32_16x16x32_bf16 v[130:133], v[134:137], v[200:203], v[130:133]
	v_mfma_f32_16x16x32_bf16 v[126:129], v[142:145], v[200:203], v[126:129]
	v_mfma_f32_16x16x32_bf16 v[114:117], v[134:137], v[208:211], v[114:117]
	v_mfma_f32_16x16x32_bf16 v[110:113], v[142:145], v[208:211], v[110:113]
	v_mfma_f32_16x16x32_bf16 v[98:101], v[134:137], v[216:219], v[98:101]
	v_mfma_f32_16x16x32_bf16 v[94:97], v[142:145], v[216:219], v[94:97]
	v_mfma_f32_16x16x32_bf16 v[78:81], v[134:137], v[224:227], v[78:81]
	v_mfma_f32_16x16x32_bf16 v[74:77], v[142:145], v[224:227], v[74:77]
	v_mfma_f32_16x16x32_bf16 v[130:133], v[138:141], v[204:207], v[130:133]
	v_mfma_f32_16x16x32_bf16 v[126:129], v[146:149], v[204:207], v[126:129]
	v_mfma_f32_16x16x32_bf16 v[114:117], v[138:141], v[212:215], v[114:117]
	v_mfma_f32_16x16x32_bf16 v[110:113], v[146:149], v[212:215], v[110:113]
	v_mfma_f32_16x16x32_bf16 v[98:101], v[138:141], v[220:223], v[98:101]
	v_mfma_f32_16x16x32_bf16 v[94:97], v[146:149], v[220:223], v[94:97]
	v_mfma_f32_16x16x32_bf16 v[78:81], v[138:141], v[228:231], v[78:81]
	v_mfma_f32_16x16x32_bf16 v[74:77], v[146:149], v[228:231], v[74:77]
	v_mfma_f32_16x16x32_bf16 v[122:125], v[166:169], v[200:203], v[122:125]
	v_mfma_f32_16x16x32_bf16 v[118:121], v[174:177], v[200:203], v[118:121]
	v_mfma_f32_16x16x32_bf16 v[106:109], v[166:169], v[208:211], v[106:109]
	v_mfma_f32_16x16x32_bf16 v[102:105], v[174:177], v[208:211], v[102:105]
	v_mfma_f32_16x16x32_bf16 v[90:93], v[166:169], v[216:219], v[90:93]
	v_mfma_f32_16x16x32_bf16 v[86:89], v[174:177], v[216:219], v[86:89]
	v_mfma_f32_16x16x32_bf16 v[70:73], v[166:169], v[224:227], v[70:73]
	v_mfma_f32_16x16x32_bf16 v[66:69], v[174:177], v[224:227], v[66:69]
	v_mfma_f32_16x16x32_bf16 v[122:125], v[170:173], v[204:207], v[122:125]
	v_mfma_f32_16x16x32_bf16 v[118:121], v[182:185], v[204:207], v[118:121]
	v_mfma_f32_16x16x32_bf16 v[106:109], v[170:173], v[212:215], v[106:109]
	v_mfma_f32_16x16x32_bf16 v[102:105], v[182:185], v[212:215], v[102:105]
	v_mfma_f32_16x16x32_bf16 v[90:93], v[170:173], v[220:223], v[90:93]
	v_mfma_f32_16x16x32_bf16 v[86:89], v[182:185], v[220:223], v[86:89]
	v_mfma_f32_16x16x32_bf16 v[70:73], v[170:173], v[228:231], v[70:73]
	v_mfma_f32_16x16x32_bf16 v[66:69], v[182:185], v[228:231], v[66:69]
	s_setprio 0
	s_barrier
; #define PG8_STAGE(bufoff, gbase, voff) do { _Pragma("unroll") for (int _i = 0; _i < 2; ++_i) \
;         __builtin_amdgcn_global_load_lds((const unsigned*)((const char*)(gbase) + (voff)[_i]), (PG8_LAS unsigned*)(lds + (bufoff) + ldsw + _i * 8192), 16, 0, 0); } while (0)
; #define PG8_LDA(dst, b, h) do { _Pragma("unroll") for (int m = 0; m < 4; ++m) _Pragma("unroll") for (int k = 0; k < 2; ++k) dst[m][k] = *(const PG8_LAS bf16x8*)(lds + PG8_SA(b, h) + aoff + m * 2048 + k * 1024); } while (0)
; #define PG8_MMA(ai, bj, At, Bt) do { __builtin_amdgcn_s_setprio(1); _Pragma("unroll") for (int m = 0; m < 4; ++m) _Pragma("unroll") for (int n = 0; n < 2; ++n) _Pragma("unroll") for (int k = 0; k < 2; ++k) \
;         acc[ai][bj][m][n] = __builtin_amdgcn_mfma_f32_16x16x32_bf16(Bt[n][k], At[m][k], acc[ai][bj][m][n], 0, 0, 0); __builtin_amdgcn_s_setprio(0); } while (0)
; #define PG8_WAIT_V(n) asm volatile("s_waitcnt vmcnt(" #n ")" ::: "memory")
; #define PG8_WAIT_L(n) asm volatile("s_waitcnt lgkmcnt(" #n ")" ::: "memory")
; #define PG8_BAR __builtin_amdgcn_s_barrier()
; #define PG8_SCHED __builtin_amdgcn_sched_barrier(0)
; template <class Epi, class Sched, bool ALIGN_EPI = false, bool SP2 = false>
; __device__ __forceinline__ void gemm_phase(PG8_LAS unsigned char* lds, const Gemm g, const Sched& S, const Epi& E) {
;     ...
;             PG8_LDA(At, 1, 1); PG8_STAGE(PG8_SB(1, 0), b3, voffB); PG8_STAGE(PG8_SB(1, 1), b3 + hstep, voffB); PG8_STAGE(PG8_SA(1, 0), a3, voffA);
;             PG8_WAIT_V(8); PG8_WAIT_L(0); PG8_BAR; PG8_MMA(1, 0, At, B0); PG8_MMA(1, 1, At, B1); PG8_BAR; PG8_SCHED;
;     ...
;         if constexpr (ALIGN_EPI) { if (wr == 0) PG8_BAR; }
	s_add_i32 s78, s80, s36
	v_lshl_add_u64 v[186:187], v[186:187], 0, s[38:39]
	s_mov_b32 m0, s78
	ds_read_b128 v[200:203], v180 offset:49152
	ds_read_b128 v[204:207], v180 offset:50176
	ds_read_b128 v[208:211], v180 offset:51200
	ds_read_b128 v[212:215], v180 offset:52224
	ds_read_b128 v[216:219], v180 offset:53248
	ds_read_b128 v[220:223], v180 offset:54272
	ds_read_b128 v[224:227], v180 offset:55296
	ds_read_b128 v[228:231], v180 offset:56320
	global_load_lds_dwordx4 v[186:187], off
	s_add_i32 m0, s78, 0x2000
	s_add_u32 s76, s76, 0x40080
	v_lshl_add_u64 v[186:187], v[232:233], 0, s[38:39]
	s_addc_u32 s77, s77, 0
	s_add_i32 s78, s81, s36
	global_load_lds_dwordx4 v[186:187], off
	s_mov_b32 m0, s78
	s_nop 0
	global_load_lds_dwordx4 v152, s[76:77]
	s_add_i32 m0, s78, 0x2000
	s_nop 0
	global_load_lds_dwordx4 v156, s[76:77]
	v_lshl_add_u64 v[186:187], v[234:235], 0, s[38:39]
	s_mov_b32 m0, s56
	s_nop 0
	global_load_lds_dwordx4 v[186:187], off
	v_lshl_add_u64 v[186:187], v[236:237], 0, s[38:39]
	s_mov_b32 m0, s75
	s_nop 0
	global_load_lds_dwordx4 v[186:187], off
	s_waitcnt vmcnt(8)
	s_waitcnt lgkmcnt(0)
	s_barrier
	s_setprio 1
	v_mfma_f32_16x16x32_bf16 v[62:65], v[134:137], v[200:203], v[62:65]
	v_mfma_f32_16x16x32_bf16 v[58:61], v[142:145], v[200:203], v[58:61]
	v_mfma_f32_16x16x32_bf16 v[46:49], v[134:137], v[208:211], v[46:49]
	v_mfma_f32_16x16x32_bf16 v[42:45], v[142:145], v[208:211], v[42:45]
	v_mfma_f32_16x16x32_bf16 v[30:33], v[134:137], v[216:219], v[30:33]
	v_mfma_f32_16x16x32_bf16 v[26:29], v[142:145], v[216:219], v[26:29]
	v_mfma_f32_16x16x32_bf16 v[14:17], v[134:137], v[224:227], v[14:17]
	v_mfma_f32_16x16x32_bf16 v[10:13], v[142:145], v[224:227], v[10:13]
	v_mfma_f32_16x16x32_bf16 v[62:65], v[138:141], v[204:207], v[62:65]
	v_mfma_f32_16x16x32_bf16 v[58:61], v[146:149], v[204:207], v[58:61]
	v_mfma_f32_16x16x32_bf16 v[46:49], v[138:141], v[212:215], v[46:49]
	v_mfma_f32_16x16x32_bf16 v[42:45], v[146:149], v[212:215], v[42:45]
	v_mfma_f32_16x16x32_bf16 v[30:33], v[138:141], v[220:223], v[30:33]
	v_mfma_f32_16x16x32_bf16 v[26:29], v[146:149], v[220:223], v[26:29]
	v_mfma_f32_16x16x32_bf16 v[14:17], v[138:141], v[228:231], v[14:17]
	v_mfma_f32_16x16x32_bf16 v[10:13], v[146:149], v[228:231], v[10:13]
	v_mfma_f32_16x16x32_bf16 v[54:57], v[166:169], v[200:203], v[54:57]
	v_mfma_f32_16x16x32_bf16 v[50:53], v[174:177], v[200:203], v[50:53]
	v_mfma_f32_16x16x32_bf16 v[38:41], v[166:169], v[208:211], v[38:41]
	v_mfma_f32_16x16x32_bf16 v[34:37], v[174:177], v[208:211], v[34:37]
	v_mfma_f32_16x16x32_bf16 v[22:25], v[166:169], v[216:219], v[22:25]
	v_mfma_f32_16x16x32_bf16 v[18:21], v[174:177], v[216:219], v[18:21]
	v_mfma_f32_16x16x32_bf16 v[6:9], v[166:169], v[224:227], v[6:9]
	v_mfma_f32_16x16x32_bf16 v[2:5], v[174:177], v[224:227], v[2:5]
	v_mfma_f32_16x16x32_bf16 v[54:57], v[170:173], v[204:207], v[54:57]
	v_mfma_f32_16x16x32_bf16 v[50:53], v[182:185], v[204:207], v[50:53]
	v_mfma_f32_16x16x32_bf16 v[38:41], v[170:173], v[212:215], v[38:41]
	v_mfma_f32_16x16x32_bf16 v[34:37], v[182:185], v[212:215], v[34:37]
	v_mfma_f32_16x16x32_bf16 v[22:25], v[170:173], v[220:223], v[22:25]
	v_mfma_f32_16x16x32_bf16 v[18:21], v[182:185], v[220:223], v[18:21]
	v_mfma_f32_16x16x32_bf16 v[6:9], v[170:173], v[228:231], v[6:9]
	v_mfma_f32_16x16x32_bf16 v[2:5], v[182:185], v[228:231], v[2:5]
	s_setprio 0
	s_barrier
	s_add_i32 s69, s69, 2
	s_add_u32 s41, s41, 0x100
	s_addc_u32 s67, s67, 0
	s_add_u32 s12, s12, 0x100
	s_addc_u32 s13, s13, 0
	s_cmp_gt_u32 s69, 13
	s_cbranch_scc0 .LBB0_111
	s_and_b64 vcc, exec, s[64:65]
	s_cbranch_vccz .LBB0_114
	s_barrier

; #define PG8_STAGE(bufoff, gbase, voff) do { _Pragma("unroll") for (int _i = 0; _i < 2; ++_i) \
;         __builtin_amdgcn_global_load_lds((const unsigned*)((const char*)(gbase) + (voff)[_i]), (PG8_LAS unsigned*)(lds + (bufoff) + ldsw + _i * 8192), 16, 0, 0); } while (0)
; #define PG8_LDA(dst, b, h) do { _Pragma("unroll") for (int m = 0; m < 4; ++m) _Pragma("unroll") for (int k = 0; k < 2; ++k) dst[m][k] = *(const PG8_LAS bf16x8*)(lds + PG8_SA(b, h) + aoff + m * 2048 + k * 1024); } while (0)
; #define PG8_LDB(dst, b, h) do { _Pragma("unroll") for (int n = 0; n < 2; ++n) _Pragma("unroll") for (int k = 0; k < 2; ++k) dst[n][k] = *(const PG8_LAS bf16x8*)(lds + PG8_SB(b, h) + boff + n * 2048 + k * 1024); } while (0)
; #define PG8_MMA(ai, bj, At, Bt) do { __builtin_amdgcn_s_setprio(1); _Pragma("unroll") for (int m = 0; m < 4; ++m) _Pragma("unroll") for (int n = 0; n < 2; ++n) _Pragma("unroll") for (int k = 0; k < 2; ++k) \
;         acc[ai][bj][m][n] = __builtin_amdgcn_mfma_f32_16x16x32_bf16(Bt[n][k], At[m][k], acc[ai][bj][m][n], 0, 0, 0); __builtin_amdgcn_s_setprio(0); } while (0)
; #define PG8_WAIT_V(n) asm volatile("s_waitcnt vmcnt(" #n ")" ::: "memory")
; #define PG8_WAIT_L(n) asm volatile("s_waitcnt lgkmcnt(" #n ")" ::: "memory")
; template <class Epi, class Sched, bool ALIGN_EPI = false, bool SP2 = false>
; __device__ __forceinline__ void gemm_phase(PG8_LAS unsigned char* lds, const Gemm g, const Sched& S, const Epi& E) {
;     ...
;             const bool last = (t == nt - 2);
;             const char* a1 = cA + (size_t)(t + 1) * kstep;
;             const char* a2 = last ? nA : cA + (size_t)(t + 2) * kstep; const char* b2 = last ? nB : cB + (size_t)(t + 2) * kstep;
;             const char* a3 = a2 + kstep; const char* b3 = b2 + kstep;
;             if (last && has_next) S.a_ready(nxt);
;             if constexpr (SP2) {
;             PG8_LDB(B0, 0, 0); PG8_LDB(B1, 0, 1); PG8_SCHED; PG8_LDA(At, 0, 0); PG8_STAGE(PG8_SA(1, 1), a1 + hstep, voffA);
;             PG8_WAIT_V(8); PG8_WAIT_L(0); PG8_BAR; PG8_MMA(0, 0, At, B0); PG8_MMA(0, 1, At, B1); PG8_BAR; PG8_SCHED;
;             PG8_LDA(At, 0, 1); PG8_STAGE(PG8_SB(0, 0), b2, voffB); PG8_STAGE(PG8_SB(0, 1), b2 + hstep, voffB); PG8_STAGE(PG8_SA(0, 0), a2, voffA);
;             PG8_WAIT_V(8); PG8_WAIT_L(0); PG8_BAR; PG8_MMA(1, 0, At, B0); PG8_MMA(1, 1, At, B1); PG8_BAR; PG8_SCHED;
.LBB0_684:
	s_add_u32 s24, s20, 0x100
	s_addc_u32 s25, s21, 0
	s_add_i32 s63, 0, 0x10000
	s_cmp_eq_u32 s62, 16
	s_cselect_b32 s59, s7, s25
	s_cselect_b32 s58, s6, s24
	v_add_u32_e32 v150, s63, v152
	s_cselect_b32 s27, s19, s61
	s_cselect_b32 s26, s18, s41
	s_add_i32 s64, 0, 0x14000
	ds_read_b128 v[146:149], v150
	ds_read_b128 v[156:159], v150 offset:1024
	ds_read_b128 v[160:163], v150 offset:2048
	ds_read_b128 v[164:167], v150 offset:3072
	v_add_u32_e32 v150, s64, v152
	ds_read_b128 v[168:171], v150
	ds_read_b128 v[172:175], v150 offset:1024
	ds_read_b128 v[180:183], v150 offset:2048
	ds_read_b128 v[184:187], v150 offset:3072
	s_add_i32 m0, s42, 0xc000
	ds_read_b128 v[200:203], v154
	ds_read_b128 v[204:207], v154 offset:1024
	ds_read_b128 v[208:211], v154 offset:2048
	ds_read_b128 v[212:215], v154 offset:3072
	ds_read_b128 v[216:219], v154 offset:4096
	ds_read_b128 v[220:223], v154 offset:5120
	ds_read_b128 v[224:227], v154 offset:6144
	ds_read_b128 v[228:231], v154 offset:7168
	global_load_lds_dwordx4 v144, s[20:21]
	s_add_i32 m0, s42, 0xe000
	s_nop 0
	global_load_lds_dwordx4 v142, s[20:21]
	s_waitcnt vmcnt(8)
	s_waitcnt lgkmcnt(0)
	s_barrier
	s_setprio 1
	v_mfma_f32_16x16x32_bf16 v[130:133], v[146:149], v[200:203], v[130:133]
	v_mfma_f32_16x16x32_bf16 v[126:129], v[160:163], v[200:203], v[126:129]
	v_mfma_f32_16x16x32_bf16 v[114:117], v[146:149], v[208:211], v[114:117]
	v_mfma_f32_16x16x32_bf16 v[110:113], v[160:163], v[208:211], v[110:113]
	v_mfma_f32_16x16x32_bf16 v[98:101], v[146:149], v[216:219], v[98:101]
	v_mfma_f32_16x16x32_bf16 v[94:97], v[160:163], v[216:219], v[94:97]
	v_mfma_f32_16x16x32_bf16 v[78:81], v[146:149], v[224:227], v[78:81]
	v_mfma_f32_16x16x32_bf16 v[74:77], v[160:163], v[224:227], v[74:77]
	v_mfma_f32_16x16x32_bf16 v[130:133], v[156:159], v[204:207], v[130:133]
	v_mfma_f32_16x16x32_bf16 v[126:129], v[164:167], v[204:207], v[126:129]
	v_mfma_f32_16x16x32_bf16 v[114:117], v[156:159], v[212:215], v[114:117]
	v_mfma_f32_16x16x32_bf16 v[110:113], v[164:167], v[212:215], v[110:113]
	v_mfma_f32_16x16x32_bf16 v[98:101], v[156:159], v[220:223], v[98:101]
	v_mfma_f32_16x16x32_bf16 v[94:97], v[164:167], v[220:223], v[94:97]
	v_mfma_f32_16x16x32_bf16 v[78:81], v[156:159], v[228:231], v[78:81]
	v_mfma_f32_16x16x32_bf16 v[74:77], v[164:167], v[228:231], v[74:77]
	v_mfma_f32_16x16x32_bf16 v[122:125], v[168:171], v[200:203], v[122:125]
	v_mfma_f32_16x16x32_bf16 v[118:121], v[180:183], v[200:203], v[118:121]
	v_mfma_f32_16x16x32_bf16 v[106:109], v[168:171], v[208:211], v[106:109]
	v_mfma_f32_16x16x32_bf16 v[102:105], v[180:183], v[208:211], v[102:105]
	v_mfma_f32_16x16x32_bf16 v[90:93], v[168:171], v[216:219], v[90:93]
	v_mfma_f32_16x16x32_bf16 v[86:89], v[180:183], v[216:219], v[86:89]
	v_mfma_f32_16x16x32_bf16 v[70:73], v[168:171], v[224:227], v[70:73]
	v_mfma_f32_16x16x32_bf16 v[66:69], v[180:183], v[224:227], v[66:69]
	v_mfma_f32_16x16x32_bf16 v[122:125], v[172:175], v[204:207], v[122:125]
	v_mfma_f32_16x16x32_bf16 v[118:121], v[184:187], v[204:207], v[118:121]
	v_mfma_f32_16x16x32_bf16 v[106:109], v[172:175], v[212:215], v[106:109]
	v_mfma_f32_16x16x32_bf16 v[102:105], v[184:187], v[212:215], v[102:105]
	v_mfma_f32_16x16x32_bf16 v[90:93], v[172:175], v[220:223], v[90:93]
	v_mfma_f32_16x16x32_bf16 v[86:89], v[184:187], v[220:223], v[86:89]
	v_mfma_f32_16x16x32_bf16 v[70:73], v[172:175], v[228:231], v[70:73]
	v_mfma_f32_16x16x32_bf16 v[66:69], v[184:187], v[228:231], v[66:69]
	s_setprio 0
	s_barrier
	s_add_i32 s20, s63, s29
	v_lshl_add_u64 v[150:151], s[26:27], 0, v[138:139]
	s_mov_b32 m0, s20
	ds_read_b128 v[200:203], v154 offset:16384
	ds_read_b128 v[204:207], v154 offset:17408
	ds_read_b128 v[208:211], v154 offset:18432
	ds_read_b128 v[212:215], v154 offset:19456
	ds_read_b128 v[216:219], v154 offset:20480
	ds_read_b128 v[220:223], v154 offset:21504
	ds_read_b128 v[224:227], v154 offset:22528
	ds_read_b128 v[228:231], v154 offset:23552
	global_load_lds_dwordx4 v[150:151], off
	s_add_i32 m0, s20, 0x2000
	s_add_u32 s20, s26, 0x50000
	v_lshl_add_u64 v[176:177], s[26:27], 0, v[134:135]
	s_addc_u32 s21, s27, 0
	s_add_i32 s63, s64, s29
	global_load_lds_dwordx4 v[176:177], off
	s_mov_b32 m0, s63
	v_lshl_add_u64 v[234:235], s[58:59], 0, v[136:137]
	global_load_lds_dwordx4 v138, s[20:21]
	s_add_i32 m0, s63, 0x2000
	s_nop 0
	global_load_lds_dwordx4 v134, s[20:21]
	v_lshl_add_u64 v[232:233], s[58:59], 0, v[140:141]
	s_mov_b32 m0, s42
	s_nop 0
	global_load_lds_dwordx4 v[232:233], off
	s_mov_b32 m0, s48
	s_nop 0
	global_load_lds_dwordx4 v[234:235], off
	s_waitcnt vmcnt(8)
	s_waitcnt lgkmcnt(0)
	s_barrier
; #define PG8_STAGE(bufoff, gbase, voff) do { _Pragma("unroll") for (int _i = 0; _i < 2; ++_i) \
;         __builtin_amdgcn_global_load_lds((const unsigned*)((const char*)(gbase) + (voff)[_i]), (PG8_LAS unsigned*)(lds + (bufoff) + ldsw + _i * 8192), 16, 0, 0); } while (0)
; #define PG8_LDA(dst, b, h) do { _Pragma("unroll") for (int m = 0; m < 4; ++m) _Pragma("unroll") for (int k = 0; k < 2; ++k) dst[m][k] = *(const PG8_LAS bf16x8*)(lds + PG8_SA(b, h) + aoff + m * 2048 + k * 1024); } while (0)
; #define PG8_LDB(dst, b, h) do { _Pragma("unroll") for (int n = 0; n < 2; ++n) _Pragma("unroll") for (int k = 0; k < 2; ++k) dst[n][k] = *(const PG8_LAS bf16x8*)(lds + PG8_SB(b, h) + boff + n * 2048 + k * 1024); } while (0)
; #define PG8_MMA(ai, bj, At, Bt) do { __builtin_amdgcn_s_setprio(1); _Pragma("unroll") for (int m = 0; m < 4; ++m) _Pragma("unroll") for (int n = 0; n < 2; ++n) _Pragma("unroll") for (int k = 0; k < 2; ++k) \
;         acc[ai][bj][m][n] = __builtin_amdgcn_mfma_f32_16x16x32_bf16(Bt[n][k], At[m][k], acc[ai][bj][m][n], 0, 0, 0); __builtin_amdgcn_s_setprio(0); } while (0)
; #define PG8_WAIT_V(n) asm volatile("s_waitcnt vmcnt(" #n ")" ::: "memory")
; #define PG8_WAIT_L(n) asm volatile("s_waitcnt lgkmcnt(" #n ")" ::: "memory")
; #define PG8_BAR __builtin_amdgcn_s_barrier()
; #define PG8_SCHED __builtin_amdgcn_sched_barrier(0)
; template <class Epi, class Sched, bool ALIGN_EPI = false, bool SP2 = false>
; __device__ __forceinline__ void gemm_phase(PG8_LAS unsigned char* lds, const Gemm g, const Sched& S, const Epi& E) {
;     ...
;             PG8_WAIT_V(8); PG8_WAIT_L(0); PG8_BAR; PG8_MMA(1, 0, At, B0); PG8_MMA(1, 1, At, B1); PG8_BAR; PG8_SCHED;
;             PG8_LDB(B0, 1, 0); PG8_LDB(B1, 1, 1); PG8_SCHED; PG8_LDA(At, 1, 0); PG8_STAGE(PG8_SA(0, 1), a2 + hstep, voffA);
;             PG8_WAIT_V(8); PG8_WAIT_L(0); PG8_BAR; PG8_MMA(0, 0, At, B0); PG8_MMA(0, 1, At, B1); PG8_BAR; PG8_SCHED;
	s_setprio 1
	v_mfma_f32_16x16x32_bf16 v[62:65], v[146:149], v[200:203], v[62:65]
	v_mfma_f32_16x16x32_bf16 v[58:61], v[160:163], v[200:203], v[58:61]
	v_mfma_f32_16x16x32_bf16 v[46:49], v[146:149], v[208:211], v[46:49]
	v_mfma_f32_16x16x32_bf16 v[42:45], v[160:163], v[208:211], v[42:45]
	v_mfma_f32_16x16x32_bf16 v[30:33], v[146:149], v[216:219], v[30:33]
	v_mfma_f32_16x16x32_bf16 v[26:29], v[160:163], v[216:219], v[26:29]
	v_mfma_f32_16x16x32_bf16 v[14:17], v[146:149], v[224:227], v[14:17]
	v_mfma_f32_16x16x32_bf16 v[10:13], v[160:163], v[224:227], v[10:13]
	v_mfma_f32_16x16x32_bf16 v[62:65], v[156:159], v[204:207], v[62:65]
	v_mfma_f32_16x16x32_bf16 v[58:61], v[164:167], v[204:207], v[58:61]
	v_mfma_f32_16x16x32_bf16 v[46:49], v[156:159], v[212:215], v[46:49]
	v_mfma_f32_16x16x32_bf16 v[42:45], v[164:167], v[212:215], v[42:45]
	v_mfma_f32_16x16x32_bf16 v[30:33], v[156:159], v[220:223], v[30:33]
	v_mfma_f32_16x16x32_bf16 v[26:29], v[164:167], v[220:223], v[26:29]
	v_mfma_f32_16x16x32_bf16 v[14:17], v[156:159], v[228:231], v[14:17]
	v_mfma_f32_16x16x32_bf16 v[10:13], v[164:167], v[228:231], v[10:13]
	v_mfma_f32_16x16x32_bf16 v[54:57], v[168:171], v[200:203], v[54:57]
	v_mfma_f32_16x16x32_bf16 v[50:53], v[180:183], v[200:203], v[50:53]
	v_mfma_f32_16x16x32_bf16 v[38:41], v[168:171], v[208:211], v[38:41]
	v_mfma_f32_16x16x32_bf16 v[34:37], v[180:183], v[208:211], v[34:37]
	v_mfma_f32_16x16x32_bf16 v[22:25], v[168:171], v[216:219], v[22:25]
	v_mfma_f32_16x16x32_bf16 v[18:21], v[180:183], v[216:219], v[18:21]
	v_mfma_f32_16x16x32_bf16 v[6:9], v[168:171], v[224:227], v[6:9]
	v_mfma_f32_16x16x32_bf16 v[2:5], v[180:183], v[224:227], v[2:5]
	v_mfma_f32_16x16x32_bf16 v[54:57], v[172:175], v[204:207], v[54:57]
	v_mfma_f32_16x16x32_bf16 v[50:53], v[184:187], v[204:207], v[50:53]
	v_mfma_f32_16x16x32_bf16 v[38:41], v[172:175], v[212:215], v[38:41]
	v_mfma_f32_16x16x32_bf16 v[34:37], v[184:187], v[212:215], v[34:37]
	v_mfma_f32_16x16x32_bf16 v[22:25], v[172:175], v[220:223], v[22:25]
	v_mfma_f32_16x16x32_bf16 v[18:21], v[184:187], v[220:223], v[18:21]
	v_mfma_f32_16x16x32_bf16 v[6:9], v[172:175], v[228:231], v[6:9]
	v_mfma_f32_16x16x32_bf16 v[2:5], v[184:187], v[228:231], v[2:5]
	s_setprio 0
	s_barrier
	s_add_i32 s63, 0, 0x18000
	v_add_u32_e32 v155, s63, v152
	s_add_i32 s64, 0, 0x1c000
	ds_read_b128 v[146:149], v155
	ds_read_b128 v[156:159], v155 offset:1024
	ds_read_b128 v[160:163], v155 offset:2048
	ds_read_b128 v[164:167], v155 offset:3072
	v_add_u32_e32 v155, s64, v152
	ds_read_b128 v[168:171], v155
	ds_read_b128 v[172:175], v155 offset:1024
	ds_read_b128 v[180:183], v155 offset:2048
	ds_read_b128 v[184:187], v155 offset:3072
	s_add_u32 s20, s58, 0x50000
	s_addc_u32 s21, s59, 0
	s_mov_b32 m0, s49
	ds_read_b128 v[200:203], v154 offset:32768
	ds_read_b128 v[204:207], v154 offset:33792
	ds_read_b128 v[208:211], v154 offset:34816
	ds_read_b128 v[212:215], v154 offset:35840
	ds_read_b128 v[216:219], v154 offset:36864
	ds_read_b128 v[220:223], v154 offset:37888
	ds_read_b128 v[224:227], v154 offset:38912
	ds_read_b128 v[228:231], v154 offset:39936
	global_load_lds_dwordx4 v140, s[20:21]
	s_mov_b32 m0, s52
	s_nop 0
	global_load_lds_dwordx4 v136, s[20:21]
	s_waitcnt vmcnt(8)
	s_waitcnt lgkmcnt(0)
	s_barrier
	s_setprio 1
	v_mfma_f32_16x16x32_bf16 v[130:133], v[146:149], v[200:203], v[130:133]
	v_mfma_f32_16x16x32_bf16 v[126:129], v[160:163], v[200:203], v[126:129]
	v_mfma_f32_16x16x32_bf16 v[114:117], v[146:149], v[208:211], v[114:117]
	v_mfma_f32_16x16x32_bf16 v[110:113], v[160:163], v[208:211], v[110:113]
	v_mfma_f32_16x16x32_bf16 v[98:101], v[146:149], v[216:219], v[98:101]
	v_mfma_f32_16x16x32_bf16 v[94:97], v[160:163], v[216:219], v[94:97]
	v_mfma_f32_16x16x32_bf16 v[78:81], v[146:149], v[224:227], v[78:81]
	v_mfma_f32_16x16x32_bf16 v[74:77], v[160:163], v[224:227], v[74:77]
	v_mfma_f32_16x16x32_bf16 v[130:133], v[156:159], v[204:207], v[130:133]
	v_mfma_f32_16x16x32_bf16 v[126:129], v[164:167], v[204:207], v[126:129]
	v_mfma_f32_16x16x32_bf16 v[114:117], v[156:159], v[212:215], v[114:117]
	v_mfma_f32_16x16x32_bf16 v[110:113], v[164:167], v[212:215], v[110:113]
	v_mfma_f32_16x16x32_bf16 v[98:101], v[156:159], v[220:223], v[98:101]
	v_mfma_f32_16x16x32_bf16 v[94:97], v[164:167], v[220:223], v[94:97]
	v_mfma_f32_16x16x32_bf16 v[78:81], v[156:159], v[228:231], v[78:81]
	v_mfma_f32_16x16x32_bf16 v[74:77], v[164:167], v[228:231], v[74:77]
	v_mfma_f32_16x16x32_bf16 v[122:125], v[168:171], v[200:203], v[122:125]
	v_mfma_f32_16x16x32_bf16 v[118:121], v[180:183], v[200:203], v[118:121]
	v_mfma_f32_16x16x32_bf16 v[106:109], v[168:171], v[208:211], v[106:109]
	v_mfma_f32_16x16x32_bf16 v[102:105], v[180:183], v[208:211], v[102:105]
	v_mfma_f32_16x16x32_bf16 v[90:93], v[168:171], v[216:219], v[90:93]
	v_mfma_f32_16x16x32_bf16 v[86:89], v[180:183], v[216:219], v[86:89]
	v_mfma_f32_16x16x32_bf16 v[70:73], v[168:171], v[224:227], v[70:73]
	v_mfma_f32_16x16x32_bf16 v[66:69], v[180:183], v[224:227], v[66:69]
	v_mfma_f32_16x16x32_bf16 v[122:125], v[172:175], v[204:207], v[122:125]
	v_mfma_f32_16x16x32_bf16 v[118:121], v[184:187], v[204:207], v[118:121]
	v_mfma_f32_16x16x32_bf16 v[106:109], v[172:175], v[212:215], v[106:109]
	v_mfma_f32_16x16x32_bf16 v[102:105], v[184:187], v[212:215], v[102:105]
	v_mfma_f32_16x16x32_bf16 v[90:93], v[172:175], v[220:223], v[90:93]
	v_mfma_f32_16x16x32_bf16 v[86:89], v[184:187], v[220:223], v[86:89]
	v_mfma_f32_16x16x32_bf16 v[70:73], v[172:175], v[228:231], v[70:73]
	v_mfma_f32_16x16x32_bf16 v[66:69], v[184:187], v[228:231], v[66:69]
	s_setprio 0
	s_barrier
; #define PG8_STAGE(bufoff, gbase, voff) do { _Pragma("unroll") for (int _i = 0; _i < 2; ++_i) \
;         __builtin_amdgcn_global_load_lds((const unsigned*)((const char*)(gbase) + (voff)[_i]), (PG8_LAS unsigned*)(lds + (bufoff) + ldsw + _i * 8192), 16, 0, 0); } while (0)
; #define PG8_LDA(dst, b, h) do { _Pragma("unroll") for (int m = 0; m < 4; ++m) _Pragma("unroll") for (int k = 0; k < 2; ++k) dst[m][k] = *(const PG8_LAS bf16x8*)(lds + PG8_SA(b, h) + aoff + m * 2048 + k * 1024); } while (0)
; #define PG8_MMA(ai, bj, At, Bt) do { __builtin_amdgcn_s_setprio(1); _Pragma("unroll") for (int m = 0; m < 4; ++m) _Pragma("unroll") for (int n = 0; n < 2; ++n) _Pragma("unroll") for (int k = 0; k < 2; ++k) \
;         acc[ai][bj][m][n] = __builtin_amdgcn_mfma_f32_16x16x32_bf16(Bt[n][k], At[m][k], acc[ai][bj][m][n], 0, 0, 0); __builtin_amdgcn_s_setprio(0); } while (0)
; #define PG8_WAIT_V(n) asm volatile("s_waitcnt vmcnt(" #n ")" ::: "memory")
; #define PG8_WAIT_L(n) asm volatile("s_waitcnt lgkmcnt(" #n ")" ::: "memory")
; #define PG8_BAR __builtin_amdgcn_s_barrier()
; #define PG8_SCHED __builtin_amdgcn_sched_barrier(0)
; template <class Epi, class Sched, bool ALIGN_EPI = false, bool SP2 = false>
; __device__ __forceinline__ void gemm_phase(PG8_LAS unsigned char* lds, const Gemm g, const Sched& S, const Epi& E) {
;     ...
;             PG8_LDA(At, 1, 1); PG8_STAGE(PG8_SB(1, 0), b3, voffB); PG8_STAGE(PG8_SB(1, 1), b3 + hstep, voffB); PG8_STAGE(PG8_SA(1, 0), a3, voffA);
;             PG8_WAIT_V(8); PG8_WAIT_L(0); PG8_BAR; PG8_MMA(1, 0, At, B0); PG8_MMA(1, 1, At, B1); PG8_BAR; PG8_SCHED;
;     ...
;         if constexpr (ALIGN_EPI) { if (wr == 0) PG8_BAR; }
	s_add_i32 s20, s63, s29
	v_lshl_add_u64 v[150:151], v[150:151], 0, s[38:39]
	s_mov_b32 m0, s20
	ds_read_b128 v[200:203], v154 offset:49152
	ds_read_b128 v[204:207], v154 offset:50176
	ds_read_b128 v[208:211], v154 offset:51200
	ds_read_b128 v[212:215], v154 offset:52224
	ds_read_b128 v[216:219], v154 offset:53248
	ds_read_b128 v[220:223], v154 offset:54272
	ds_read_b128 v[224:227], v154 offset:55296
	ds_read_b128 v[228:231], v154 offset:56320
	global_load_lds_dwordx4 v[150:151], off
	s_add_i32 m0, s20, 0x2000
	s_add_u32 s20, s26, 0x50080
	v_lshl_add_u64 v[150:151], v[176:177], 0, s[38:39]
	s_addc_u32 s21, s27, 0
	s_add_i32 s26, s64, s29
	global_load_lds_dwordx4 v[150:151], off
	s_mov_b32 m0, s26
	s_nop 0
	global_load_lds_dwordx4 v138, s[20:21]
	s_add_i32 m0, s26, 0x2000
	s_nop 0
	global_load_lds_dwordx4 v134, s[20:21]
	v_lshl_add_u64 v[150:151], v[232:233], 0, s[38:39]
	s_mov_b32 m0, s53
	s_nop 0
	global_load_lds_dwordx4 v[150:151], off
	v_lshl_add_u64 v[150:151], v[234:235], 0, s[38:39]
	s_mov_b32 m0, s54
	s_nop 0
	global_load_lds_dwordx4 v[150:151], off
	s_waitcnt vmcnt(8)
	s_waitcnt lgkmcnt(0)
	s_barrier
	s_setprio 1
	v_mfma_f32_16x16x32_bf16 v[62:65], v[146:149], v[200:203], v[62:65]
	v_mfma_f32_16x16x32_bf16 v[58:61], v[160:163], v[200:203], v[58:61]
	v_mfma_f32_16x16x32_bf16 v[46:49], v[146:149], v[208:211], v[46:49]
	v_mfma_f32_16x16x32_bf16 v[42:45], v[160:163], v[208:211], v[42:45]
	v_mfma_f32_16x16x32_bf16 v[30:33], v[146:149], v[216:219], v[30:33]
	v_mfma_f32_16x16x32_bf16 v[26:29], v[160:163], v[216:219], v[26:29]
	v_mfma_f32_16x16x32_bf16 v[14:17], v[146:149], v[224:227], v[14:17]
	v_mfma_f32_16x16x32_bf16 v[10:13], v[160:163], v[224:227], v[10:13]
	v_mfma_f32_16x16x32_bf16 v[62:65], v[156:159], v[204:207], v[62:65]
	v_mfma_f32_16x16x32_bf16 v[58:61], v[164:167], v[204:207], v[58:61]
	v_mfma_f32_16x16x32_bf16 v[46:49], v[156:159], v[212:215], v[46:49]
	v_mfma_f32_16x16x32_bf16 v[42:45], v[164:167], v[212:215], v[42:45]
	v_mfma_f32_16x16x32_bf16 v[30:33], v[156:159], v[220:223], v[30:33]
	v_mfma_f32_16x16x32_bf16 v[26:29], v[164:167], v[220:223], v[26:29]
	v_mfma_f32_16x16x32_bf16 v[14:17], v[156:159], v[228:231], v[14:17]
	v_mfma_f32_16x16x32_bf16 v[10:13], v[164:167], v[228:231], v[10:13]
	v_mfma_f32_16x16x32_bf16 v[54:57], v[168:171], v[200:203], v[54:57]
	v_mfma_f32_16x16x32_bf16 v[50:53], v[180:183], v[200:203], v[50:53]
	v_mfma_f32_16x16x32_bf16 v[38:41], v[168:171], v[208:211], v[38:41]
	v_mfma_f32_16x16x32_bf16 v[34:37], v[180:183], v[208:211], v[34:37]
	v_mfma_f32_16x16x32_bf16 v[22:25], v[168:171], v[216:219], v[22:25]
	v_mfma_f32_16x16x32_bf16 v[18:21], v[180:183], v[216:219], v[18:21]
	v_mfma_f32_16x16x32_bf16 v[6:9], v[168:171], v[224:227], v[6:9]
	v_mfma_f32_16x16x32_bf16 v[2:5], v[180:183], v[224:227], v[2:5]
	v_mfma_f32_16x16x32_bf16 v[54:57], v[172:175], v[204:207], v[54:57]
	v_mfma_f32_16x16x32_bf16 v[50:53], v[184:187], v[204:207], v[50:53]
	v_mfma_f32_16x16x32_bf16 v[38:41], v[172:175], v[212:215], v[38:41]
	v_mfma_f32_16x16x32_bf16 v[34:37], v[184:187], v[212:215], v[34:37]
	v_mfma_f32_16x16x32_bf16 v[22:25], v[172:175], v[220:223], v[22:25]
	v_mfma_f32_16x16x32_bf16 v[18:21], v[184:187], v[220:223], v[18:21]
	v_mfma_f32_16x16x32_bf16 v[6:9], v[172:175], v[228:231], v[6:9]
	v_mfma_f32_16x16x32_bf16 v[2:5], v[184:187], v[228:231], v[2:5]
	s_setprio 0
	s_barrier
	s_add_i32 s62, s62, 2
	s_add_u32 s41, s41, 0x100
	s_addc_u32 s61, s61, 0
	s_cmp_gt_u32 s62, 17
	s_mov_b64 s[20:21], s[24:25]
	s_cbranch_scc0 .LBB0_684
	s_and_b64 vcc, exec, s[16:17]
	s_cbranch_vccz .LBB0_687
	s_barrier

; #define PG8_STAGE(bufoff, gbase, voff) do { _Pragma("unroll") for (int _i = 0; _i < 2; ++_i) \
;         __builtin_amdgcn_global_load_lds((const unsigned*)((const char*)(gbase) + (voff)[_i]), (PG8_LAS unsigned*)(lds + (bufoff) + ldsw + _i * 8192), 16, 0, 0); } while (0)
; #define PG8_LDA(dst, b, h) do { _Pragma("unroll") for (int m = 0; m < 4; ++m) _Pragma("unroll") for (int k = 0; k < 2; ++k) dst[m][k] = *(const PG8_LAS bf16x8*)(lds + PG8_SA(b, h) + aoff + m * 2048 + k * 1024); } while (0)
; #define PG8_LDB(dst, b, h) do { _Pragma("unroll") for (int n = 0; n < 2; ++n) _Pragma("unroll") for (int k = 0; k < 2; ++k) dst[n][k] = *(const PG8_LAS bf16x8*)(lds + PG8_SB(b, h) + boff + n * 2048 + k * 1024); } while (0)
; #define PG8_MMA(ai, bj, At, Bt) do { __builtin_amdgcn_s_setprio(1); _Pragma("unroll") for (int m = 0; m < 4; ++m) _Pragma("unroll") for (int n = 0; n < 2; ++n) _Pragma("unroll") for (int k = 0; k < 2; ++k) \
;         acc[ai][bj][m][n] = __builtin_amdgcn_mfma_f32_16x16x32_bf16(Bt[n][k], At[m][k], acc[ai][bj][m][n], 0, 0, 0); __builtin_amdgcn_s_setprio(0); } while (0)
; #define PG8_WAIT_V(n) asm volatile("s_waitcnt vmcnt(" #n ")" ::: "memory")
; #define PG8_WAIT_L(n) asm volatile("s_waitcnt lgkmcnt(" #n ")" ::: "memory")
; template <class Epi, class Sched, bool ALIGN_EPI = false, bool SP2 = false>
; __device__ __forceinline__ void gemm_phase(PG8_LAS unsigned char* lds, const Gemm g, const Sched& S, const Epi& E) {
;     ...
;             const bool last = (t == nt - 2);
;             const char* a1 = cA + (size_t)(t + 1) * kstep;
;             const char* a2 = last ? nA : cA + (size_t)(t + 2) * kstep; const char* b2 = last ? nB : cB + (size_t)(t + 2) * kstep;
;             const char* a3 = a2 + kstep; const char* b3 = b2 + kstep;
;             if (last && has_next) S.a_ready(nxt);
;             if constexpr (SP2) {
;             PG8_LDB(B0, 0, 0); PG8_LDB(B1, 0, 1); PG8_SCHED; PG8_LDA(At, 0, 0); PG8_STAGE(PG8_SA(1, 1), a1 + hstep, voffA);
;             PG8_WAIT_V(8); PG8_WAIT_L(0); PG8_BAR; PG8_MMA(0, 0, At, B0); PG8_MMA(0, 1, At, B1); PG8_BAR; PG8_SCHED;
;             PG8_LDA(At, 0, 1); PG8_STAGE(PG8_SB(0, 0), b2, voffB); PG8_STAGE(PG8_SB(0, 1), b2 + hstep, voffB); PG8_STAGE(PG8_SA(0, 0), a2, voffA);
;             PG8_WAIT_V(8); PG8_WAIT_L(0); PG8_BAR; PG8_MMA(1, 0, At, B0); PG8_MMA(1, 1, At, B1); PG8_BAR; PG8_SCHED;
.LBB0_700:
	s_add_u32 s59, s60, 0xfffe0080
	s_addc_u32 s62, s61, -1
	s_add_i32 s66, 0, 0x10000
	s_cmp_eq_u32 s56, 4
	s_cselect_b32 s65, s19, s62
	s_cselect_b32 s64, s23, s59
	v_add_u32_e32 v154, s66, v156
	s_cselect_b32 s63, s17, s41
	s_cselect_b32 s62, s27, s40
	s_add_i32 s59, 0, 0x14000
	ds_read_b128 v[146:149], v154
	ds_read_b128 v[150:153], v154 offset:1024
	ds_read_b128 v[160:163], v154 offset:2048
	ds_read_b128 v[164:167], v154 offset:3072
	v_add_u32_e32 v154, s59, v156
	ds_read_b128 v[168:171], v154
	ds_read_b128 v[172:175], v154 offset:1024
	ds_read_b128 v[180:183], v154 offset:2048
	ds_read_b128 v[184:187], v154 offset:3072
	s_add_i32 m0, s42, 0xc000
	ds_read_b128 v[200:203], v158
	ds_read_b128 v[204:207], v158 offset:1024
	ds_read_b128 v[208:211], v158 offset:2048
	ds_read_b128 v[212:215], v158 offset:3072
	ds_read_b128 v[216:219], v158 offset:4096
	ds_read_b128 v[220:223], v158 offset:5120
	ds_read_b128 v[224:227], v158 offset:6144
	ds_read_b128 v[228:231], v158 offset:7168
	global_load_lds_dwordx4 v144, s[60:61]
	s_add_i32 m0, s42, 0xe000
	s_nop 0
	global_load_lds_dwordx4 v142, s[60:61]
	s_waitcnt vmcnt(8)
	s_waitcnt lgkmcnt(0)
	s_barrier
	s_setprio 1
	v_mfma_f32_16x16x32_bf16 v[130:133], v[146:149], v[200:203], v[130:133]
	v_mfma_f32_16x16x32_bf16 v[126:129], v[160:163], v[200:203], v[126:129]
	v_mfma_f32_16x16x32_bf16 v[114:117], v[146:149], v[208:211], v[114:117]
	v_mfma_f32_16x16x32_bf16 v[110:113], v[160:163], v[208:211], v[110:113]
	v_mfma_f32_16x16x32_bf16 v[98:101], v[146:149], v[216:219], v[98:101]
	v_mfma_f32_16x16x32_bf16 v[94:97], v[160:163], v[216:219], v[94:97]
	v_mfma_f32_16x16x32_bf16 v[78:81], v[146:149], v[224:227], v[78:81]
	v_mfma_f32_16x16x32_bf16 v[74:77], v[160:163], v[224:227], v[74:77]
	v_mfma_f32_16x16x32_bf16 v[130:133], v[150:153], v[204:207], v[130:133]
	v_mfma_f32_16x16x32_bf16 v[126:129], v[164:167], v[204:207], v[126:129]
	v_mfma_f32_16x16x32_bf16 v[114:117], v[150:153], v[212:215], v[114:117]
	v_mfma_f32_16x16x32_bf16 v[110:113], v[164:167], v[212:215], v[110:113]
	v_mfma_f32_16x16x32_bf16 v[98:101], v[150:153], v[220:223], v[98:101]
	v_mfma_f32_16x16x32_bf16 v[94:97], v[164:167], v[220:223], v[94:97]
	v_mfma_f32_16x16x32_bf16 v[78:81], v[150:153], v[228:231], v[78:81]
	v_mfma_f32_16x16x32_bf16 v[74:77], v[164:167], v[228:231], v[74:77]
	v_mfma_f32_16x16x32_bf16 v[122:125], v[168:171], v[200:203], v[122:125]
	v_mfma_f32_16x16x32_bf16 v[118:121], v[180:183], v[200:203], v[118:121]
	v_mfma_f32_16x16x32_bf16 v[106:109], v[168:171], v[208:211], v[106:109]
	v_mfma_f32_16x16x32_bf16 v[102:105], v[180:183], v[208:211], v[102:105]
	v_mfma_f32_16x16x32_bf16 v[90:93], v[168:171], v[216:219], v[90:93]
	v_mfma_f32_16x16x32_bf16 v[86:89], v[180:183], v[216:219], v[86:89]
	v_mfma_f32_16x16x32_bf16 v[70:73], v[168:171], v[224:227], v[70:73]
	v_mfma_f32_16x16x32_bf16 v[66:69], v[180:183], v[224:227], v[66:69]
	v_mfma_f32_16x16x32_bf16 v[122:125], v[172:175], v[204:207], v[122:125]
	v_mfma_f32_16x16x32_bf16 v[118:121], v[184:187], v[204:207], v[118:121]
	v_mfma_f32_16x16x32_bf16 v[106:109], v[172:175], v[212:215], v[106:109]
	v_mfma_f32_16x16x32_bf16 v[102:105], v[184:187], v[212:215], v[102:105]
	v_mfma_f32_16x16x32_bf16 v[90:93], v[172:175], v[220:223], v[90:93]
	v_mfma_f32_16x16x32_bf16 v[86:89], v[184:187], v[220:223], v[86:89]
	v_mfma_f32_16x16x32_bf16 v[70:73], v[172:175], v[228:231], v[70:73]
	v_mfma_f32_16x16x32_bf16 v[66:69], v[184:187], v[228:231], v[66:69]
	s_setprio 0
	s_barrier
	s_add_i32 s66, s66, s29
	v_lshl_add_u64 v[154:155], s[62:63], 0, v[138:139]
	s_mov_b32 m0, s66
	ds_read_b128 v[200:203], v158 offset:16384
	ds_read_b128 v[204:207], v158 offset:17408
	ds_read_b128 v[208:211], v158 offset:18432
	ds_read_b128 v[212:215], v158 offset:19456
	ds_read_b128 v[216:219], v158 offset:20480
	ds_read_b128 v[220:223], v158 offset:21504
	ds_read_b128 v[224:227], v158 offset:22528
	ds_read_b128 v[228:231], v158 offset:23552
	global_load_lds_dwordx4 v[154:155], off
	s_add_i32 m0, s66, 0x2000
	s_add_u32 s66, s62, 0x20000
	v_lshl_add_u64 v[176:177], s[62:63], 0, v[134:135]
	s_addc_u32 s67, s63, 0
	s_add_i32 s59, s59, s29
	global_load_lds_dwordx4 v[176:177], off
	s_mov_b32 m0, s59
	v_lshl_add_u64 v[234:235], s[64:65], 0, v[136:137]
	global_load_lds_dwordx4 v138, s[66:67]
	s_add_i32 m0, s59, 0x2000
	s_nop 0
	global_load_lds_dwordx4 v134, s[66:67]
	v_lshl_add_u64 v[232:233], s[64:65], 0, v[140:141]
	s_mov_b32 m0, s42
	s_nop 0
	global_load_lds_dwordx4 v[232:233], off
	s_mov_b32 m0, s48
	s_nop 0
	global_load_lds_dwordx4 v[234:235], off
	s_waitcnt vmcnt(8)
	s_waitcnt lgkmcnt(0)
	s_barrier
; #define PG8_STAGE(bufoff, gbase, voff) do { _Pragma("unroll") for (int _i = 0; _i < 2; ++_i) \
;         __builtin_amdgcn_global_load_lds((const unsigned*)((const char*)(gbase) + (voff)[_i]), (PG8_LAS unsigned*)(lds + (bufoff) + ldsw + _i * 8192), 16, 0, 0); } while (0)
; #define PG8_LDA(dst, b, h) do { _Pragma("unroll") for (int m = 0; m < 4; ++m) _Pragma("unroll") for (int k = 0; k < 2; ++k) dst[m][k] = *(const PG8_LAS bf16x8*)(lds + PG8_SA(b, h) + aoff + m * 2048 + k * 1024); } while (0)
; #define PG8_LDB(dst, b, h) do { _Pragma("unroll") for (int n = 0; n < 2; ++n) _Pragma("unroll") for (int k = 0; k < 2; ++k) dst[n][k] = *(const PG8_LAS bf16x8*)(lds + PG8_SB(b, h) + boff + n * 2048 + k * 1024); } while (0)
; #define PG8_MMA(ai, bj, At, Bt) do { __builtin_amdgcn_s_setprio(1); _Pragma("unroll") for (int m = 0; m < 4; ++m) _Pragma("unroll") for (int n = 0; n < 2; ++n) _Pragma("unroll") for (int k = 0; k < 2; ++k) \
;         acc[ai][bj][m][n] = __builtin_amdgcn_mfma_f32_16x16x32_bf16(Bt[n][k], At[m][k], acc[ai][bj][m][n], 0, 0, 0); __builtin_amdgcn_s_setprio(0); } while (0)
; #define PG8_WAIT_V(n) asm volatile("s_waitcnt vmcnt(" #n ")" ::: "memory")
; #define PG8_WAIT_L(n) asm volatile("s_waitcnt lgkmcnt(" #n ")" ::: "memory")
; #define PG8_BAR __builtin_amdgcn_s_barrier()
; #define PG8_SCHED __builtin_amdgcn_sched_barrier(0)
; template <class Epi, class Sched, bool ALIGN_EPI = false, bool SP2 = false>
; __device__ __forceinline__ void gemm_phase(PG8_LAS unsigned char* lds, const Gemm g, const Sched& S, const Epi& E) {
;     ...
;             PG8_WAIT_V(8); PG8_WAIT_L(0); PG8_BAR; PG8_MMA(1, 0, At, B0); PG8_MMA(1, 1, At, B1); PG8_BAR; PG8_SCHED;
;             PG8_LDB(B0, 1, 0); PG8_LDB(B1, 1, 1); PG8_SCHED; PG8_LDA(At, 1, 0); PG8_STAGE(PG8_SA(0, 1), a2 + hstep, voffA);
;             PG8_WAIT_V(8); PG8_WAIT_L(0); PG8_BAR; PG8_MMA(0, 0, At, B0); PG8_MMA(0, 1, At, B1); PG8_BAR; PG8_SCHED;
	s_setprio 1
	v_mfma_f32_16x16x32_bf16 v[62:65], v[146:149], v[200:203], v[62:65]
	v_mfma_f32_16x16x32_bf16 v[58:61], v[160:163], v[200:203], v[58:61]
	v_mfma_f32_16x16x32_bf16 v[46:49], v[146:149], v[208:211], v[46:49]
	v_mfma_f32_16x16x32_bf16 v[42:45], v[160:163], v[208:211], v[42:45]
	v_mfma_f32_16x16x32_bf16 v[30:33], v[146:149], v[216:219], v[30:33]
	v_mfma_f32_16x16x32_bf16 v[26:29], v[160:163], v[216:219], v[26:29]
	v_mfma_f32_16x16x32_bf16 v[14:17], v[146:149], v[224:227], v[14:17]
	v_mfma_f32_16x16x32_bf16 v[10:13], v[160:163], v[224:227], v[10:13]
	v_mfma_f32_16x16x32_bf16 v[62:65], v[150:153], v[204:207], v[62:65]
	v_mfma_f32_16x16x32_bf16 v[58:61], v[164:167], v[204:207], v[58:61]
	v_mfma_f32_16x16x32_bf16 v[46:49], v[150:153], v[212:215], v[46:49]
	v_mfma_f32_16x16x32_bf16 v[42:45], v[164:167], v[212:215], v[42:45]
	v_mfma_f32_16x16x32_bf16 v[30:33], v[150:153], v[220:223], v[30:33]
	v_mfma_f32_16x16x32_bf16 v[26:29], v[164:167], v[220:223], v[26:29]
	v_mfma_f32_16x16x32_bf16 v[14:17], v[150:153], v[228:231], v[14:17]
	v_mfma_f32_16x16x32_bf16 v[10:13], v[164:167], v[228:231], v[10:13]
	v_mfma_f32_16x16x32_bf16 v[54:57], v[168:171], v[200:203], v[54:57]
	v_mfma_f32_16x16x32_bf16 v[50:53], v[180:183], v[200:203], v[50:53]
	v_mfma_f32_16x16x32_bf16 v[38:41], v[168:171], v[208:211], v[38:41]
	v_mfma_f32_16x16x32_bf16 v[34:37], v[180:183], v[208:211], v[34:37]
	v_mfma_f32_16x16x32_bf16 v[22:25], v[168:171], v[216:219], v[22:25]
	v_mfma_f32_16x16x32_bf16 v[18:21], v[180:183], v[216:219], v[18:21]
	v_mfma_f32_16x16x32_bf16 v[6:9], v[168:171], v[224:227], v[6:9]
	v_mfma_f32_16x16x32_bf16 v[2:5], v[180:183], v[224:227], v[2:5]
	v_mfma_f32_16x16x32_bf16 v[54:57], v[172:175], v[204:207], v[54:57]
	v_mfma_f32_16x16x32_bf16 v[50:53], v[184:187], v[204:207], v[50:53]
	v_mfma_f32_16x16x32_bf16 v[38:41], v[172:175], v[212:215], v[38:41]
	v_mfma_f32_16x16x32_bf16 v[34:37], v[184:187], v[212:215], v[34:37]
	v_mfma_f32_16x16x32_bf16 v[22:25], v[172:175], v[220:223], v[22:25]
	v_mfma_f32_16x16x32_bf16 v[18:21], v[184:187], v[220:223], v[18:21]
	v_mfma_f32_16x16x32_bf16 v[6:9], v[172:175], v[228:231], v[6:9]
	v_mfma_f32_16x16x32_bf16 v[2:5], v[184:187], v[228:231], v[2:5]
	s_setprio 0
	s_barrier
	s_add_i32 s59, 0, 0x18000
	v_add_u32_e32 v159, s59, v156
	s_add_i32 s66, 0, 0x1c000
	ds_read_b128 v[146:149], v159
	ds_read_b128 v[150:153], v159 offset:1024
	ds_read_b128 v[160:163], v159 offset:2048
	ds_read_b128 v[164:167], v159 offset:3072
	v_add_u32_e32 v159, s66, v156
	ds_read_b128 v[168:171], v159
	ds_read_b128 v[172:175], v159 offset:1024
	ds_read_b128 v[180:183], v159 offset:2048
	ds_read_b128 v[184:187], v159 offset:3072
	s_add_u32 s64, s64, 0x20000
	s_addc_u32 s65, s65, 0
	s_mov_b32 m0, s49
	ds_read_b128 v[200:203], v158 offset:32768
	ds_read_b128 v[204:207], v158 offset:33792
	ds_read_b128 v[208:211], v158 offset:34816
	ds_read_b128 v[212:215], v158 offset:35840
	ds_read_b128 v[216:219], v158 offset:36864
	ds_read_b128 v[220:223], v158 offset:37888
	ds_read_b128 v[224:227], v158 offset:38912
	ds_read_b128 v[228:231], v158 offset:39936
	global_load_lds_dwordx4 v140, s[64:65]
	s_mov_b32 m0, s52
	s_nop 0
	global_load_lds_dwordx4 v136, s[64:65]
	s_waitcnt vmcnt(8)
	s_waitcnt lgkmcnt(0)
	s_barrier
	s_setprio 1
	v_mfma_f32_16x16x32_bf16 v[130:133], v[146:149], v[200:203], v[130:133]
	v_mfma_f32_16x16x32_bf16 v[126:129], v[160:163], v[200:203], v[126:129]
	v_mfma_f32_16x16x32_bf16 v[114:117], v[146:149], v[208:211], v[114:117]
	v_mfma_f32_16x16x32_bf16 v[110:113], v[160:163], v[208:211], v[110:113]
	v_mfma_f32_16x16x32_bf16 v[98:101], v[146:149], v[216:219], v[98:101]
	v_mfma_f32_16x16x32_bf16 v[94:97], v[160:163], v[216:219], v[94:97]
	v_mfma_f32_16x16x32_bf16 v[78:81], v[146:149], v[224:227], v[78:81]
	v_mfma_f32_16x16x32_bf16 v[74:77], v[160:163], v[224:227], v[74:77]
	v_mfma_f32_16x16x32_bf16 v[130:133], v[150:153], v[204:207], v[130:133]
	v_mfma_f32_16x16x32_bf16 v[126:129], v[164:167], v[204:207], v[126:129]
	v_mfma_f32_16x16x32_bf16 v[114:117], v[150:153], v[212:215], v[114:117]
	v_mfma_f32_16x16x32_bf16 v[110:113], v[164:167], v[212:215], v[110:113]
	v_mfma_f32_16x16x32_bf16 v[98:101], v[150:153], v[220:223], v[98:101]
	v_mfma_f32_16x16x32_bf16 v[94:97], v[164:167], v[220:223], v[94:97]
	v_mfma_f32_16x16x32_bf16 v[78:81], v[150:153], v[228:231], v[78:81]
	v_mfma_f32_16x16x32_bf16 v[74:77], v[164:167], v[228:231], v[74:77]
	v_mfma_f32_16x16x32_bf16 v[122:125], v[168:171], v[200:203], v[122:125]
	v_mfma_f32_16x16x32_bf16 v[118:121], v[180:183], v[200:203], v[118:121]
	v_mfma_f32_16x16x32_bf16 v[106:109], v[168:171], v[208:211], v[106:109]
	v_mfma_f32_16x16x32_bf16 v[102:105], v[180:183], v[208:211], v[102:105]
	v_mfma_f32_16x16x32_bf16 v[90:93], v[168:171], v[216:219], v[90:93]
	v_mfma_f32_16x16x32_bf16 v[86:89], v[180:183], v[216:219], v[86:89]
	v_mfma_f32_16x16x32_bf16 v[70:73], v[168:171], v[224:227], v[70:73]
	v_mfma_f32_16x16x32_bf16 v[66:69], v[180:183], v[224:227], v[66:69]
	v_mfma_f32_16x16x32_bf16 v[122:125], v[172:175], v[204:207], v[122:125]
	v_mfma_f32_16x16x32_bf16 v[118:121], v[184:187], v[204:207], v[118:121]
	v_mfma_f32_16x16x32_bf16 v[106:109], v[172:175], v[212:215], v[106:109]
	v_mfma_f32_16x16x32_bf16 v[102:105], v[184:187], v[212:215], v[102:105]
	v_mfma_f32_16x16x32_bf16 v[90:93], v[172:175], v[220:223], v[90:93]
	v_mfma_f32_16x16x32_bf16 v[86:89], v[184:187], v[220:223], v[86:89]
	v_mfma_f32_16x16x32_bf16 v[70:73], v[172:175], v[228:231], v[70:73]
	v_mfma_f32_16x16x32_bf16 v[66:69], v[184:187], v[228:231], v[66:69]
	s_setprio 0
	s_barrier
; #define PG8_STAGE(bufoff, gbase, voff) do { _Pragma("unroll") for (int _i = 0; _i < 2; ++_i) \
;         __builtin_amdgcn_global_load_lds((const unsigned*)((const char*)(gbase) + (voff)[_i]), (PG8_LAS unsigned*)(lds + (bufoff) + ldsw + _i * 8192), 16, 0, 0); } while (0)
; #define PG8_LDA(dst, b, h) do { _Pragma("unroll") for (int m = 0; m < 4; ++m) _Pragma("unroll") for (int k = 0; k < 2; ++k) dst[m][k] = *(const PG8_LAS bf16x8*)(lds + PG8_SA(b, h) + aoff + m * 2048 + k * 1024); } while (0)
; #define PG8_MMA(ai, bj, At, Bt) do { __builtin_amdgcn_s_setprio(1); _Pragma("unroll") for (int m = 0; m < 4; ++m) _Pragma("unroll") for (int n = 0; n < 2; ++n) _Pragma("unroll") for (int k = 0; k < 2; ++k) \
;         acc[ai][bj][m][n] = __builtin_amdgcn_mfma_f32_16x16x32_bf16(Bt[n][k], At[m][k], acc[ai][bj][m][n], 0, 0, 0); __builtin_amdgcn_s_setprio(0); } while (0)
; #define PG8_WAIT_V(n) asm volatile("s_waitcnt vmcnt(" #n ")" ::: "memory")
; #define PG8_WAIT_L(n) asm volatile("s_waitcnt lgkmcnt(" #n ")" ::: "memory")
; #define PG8_BAR __builtin_amdgcn_s_barrier()
; #define PG8_SCHED __builtin_amdgcn_sched_barrier(0)
; template <class Epi, class Sched, bool ALIGN_EPI = false, bool SP2 = false>
; __device__ __forceinline__ void gemm_phase(PG8_LAS unsigned char* lds, const Gemm g, const Sched& S, const Epi& E) {
;     ...
;             PG8_LDA(At, 1, 1); PG8_STAGE(PG8_SB(1, 0), b3, voffB); PG8_STAGE(PG8_SB(1, 1), b3 + hstep, voffB); PG8_STAGE(PG8_SA(1, 0), a3, voffA);
;             PG8_WAIT_V(8); PG8_WAIT_L(0); PG8_BAR; PG8_MMA(1, 0, At, B0); PG8_MMA(1, 1, At, B1); PG8_BAR; PG8_SCHED;
;     ...
;         if constexpr (ALIGN_EPI) { if (wr == 0) PG8_BAR; }
	s_add_i32 s59, s59, s29
	v_lshl_add_u64 v[154:155], v[154:155], 0, s[38:39]
	s_mov_b32 m0, s59
	ds_read_b128 v[200:203], v158 offset:49152
	ds_read_b128 v[204:207], v158 offset:50176
	ds_read_b128 v[208:211], v158 offset:51200
	ds_read_b128 v[212:215], v158 offset:52224
	ds_read_b128 v[216:219], v158 offset:53248
	ds_read_b128 v[220:223], v158 offset:54272
	ds_read_b128 v[224:227], v158 offset:55296
	ds_read_b128 v[228:231], v158 offset:56320
	global_load_lds_dwordx4 v[154:155], off
	s_add_i32 m0, s59, 0x2000
	s_add_u32 s62, s62, 0x20080
	v_lshl_add_u64 v[154:155], v[176:177], 0, s[38:39]
	s_addc_u32 s63, s63, 0
	s_add_i32 s59, s66, s29
	global_load_lds_dwordx4 v[154:155], off
	s_mov_b32 m0, s59
	s_nop 0
	global_load_lds_dwordx4 v138, s[62:63]
	s_add_i32 m0, s59, 0x2000
	s_nop 0
	global_load_lds_dwordx4 v134, s[62:63]
	v_lshl_add_u64 v[154:155], v[232:233], 0, s[38:39]
	s_mov_b32 m0, s53
	s_nop 0
	global_load_lds_dwordx4 v[154:155], off
	v_lshl_add_u64 v[154:155], v[234:235], 0, s[38:39]
	s_mov_b32 m0, s54
	s_nop 0
	global_load_lds_dwordx4 v[154:155], off
	s_waitcnt vmcnt(8)
	s_waitcnt lgkmcnt(0)
	s_barrier
	s_setprio 1
	v_mfma_f32_16x16x32_bf16 v[62:65], v[146:149], v[200:203], v[62:65]
	v_mfma_f32_16x16x32_bf16 v[58:61], v[160:163], v[200:203], v[58:61]
	v_mfma_f32_16x16x32_bf16 v[46:49], v[146:149], v[208:211], v[46:49]
	v_mfma_f32_16x16x32_bf16 v[42:45], v[160:163], v[208:211], v[42:45]
	v_mfma_f32_16x16x32_bf16 v[30:33], v[146:149], v[216:219], v[30:33]
	v_mfma_f32_16x16x32_bf16 v[26:29], v[160:163], v[216:219], v[26:29]
	v_mfma_f32_16x16x32_bf16 v[14:17], v[146:149], v[224:227], v[14:17]
	v_mfma_f32_16x16x32_bf16 v[10:13], v[160:163], v[224:227], v[10:13]
	v_mfma_f32_16x16x32_bf16 v[62:65], v[150:153], v[204:207], v[62:65]
	v_mfma_f32_16x16x32_bf16 v[58:61], v[164:167], v[204:207], v[58:61]
	v_mfma_f32_16x16x32_bf16 v[46:49], v[150:153], v[212:215], v[46:49]
	v_mfma_f32_16x16x32_bf16 v[42:45], v[164:167], v[212:215], v[42:45]
	v_mfma_f32_16x16x32_bf16 v[30:33], v[150:153], v[220:223], v[30:33]
	v_mfma_f32_16x16x32_bf16 v[26:29], v[164:167], v[220:223], v[26:29]
	v_mfma_f32_16x16x32_bf16 v[14:17], v[150:153], v[228:231], v[14:17]
	v_mfma_f32_16x16x32_bf16 v[10:13], v[164:167], v[228:231], v[10:13]
	v_mfma_f32_16x16x32_bf16 v[54:57], v[168:171], v[200:203], v[54:57]
	v_mfma_f32_16x16x32_bf16 v[50:53], v[180:183], v[200:203], v[50:53]
	v_mfma_f32_16x16x32_bf16 v[38:41], v[168:171], v[208:211], v[38:41]
	v_mfma_f32_16x16x32_bf16 v[34:37], v[180:183], v[208:211], v[34:37]
	v_mfma_f32_16x16x32_bf16 v[22:25], v[168:171], v[216:219], v[22:25]
	v_mfma_f32_16x16x32_bf16 v[18:21], v[180:183], v[216:219], v[18:21]
	v_mfma_f32_16x16x32_bf16 v[6:9], v[168:171], v[224:227], v[6:9]
	v_mfma_f32_16x16x32_bf16 v[2:5], v[180:183], v[224:227], v[2:5]
	v_mfma_f32_16x16x32_bf16 v[54:57], v[172:175], v[204:207], v[54:57]
	v_mfma_f32_16x16x32_bf16 v[50:53], v[184:187], v[204:207], v[50:53]
	v_mfma_f32_16x16x32_bf16 v[38:41], v[172:175], v[212:215], v[38:41]
	v_mfma_f32_16x16x32_bf16 v[34:37], v[184:187], v[212:215], v[34:37]
	v_mfma_f32_16x16x32_bf16 v[22:25], v[172:175], v[220:223], v[22:25]
	v_mfma_f32_16x16x32_bf16 v[18:21], v[184:187], v[220:223], v[18:21]
	v_mfma_f32_16x16x32_bf16 v[6:9], v[172:175], v[228:231], v[6:9]
	v_mfma_f32_16x16x32_bf16 v[2:5], v[184:187], v[228:231], v[2:5]
	s_setprio 0
	s_barrier
	s_add_i32 s56, s56, 2
	s_add_u32 s40, s40, 0x100
	s_addc_u32 s41, s41, 0
	s_add_u32 s60, s60, 0x100
	s_addc_u32 s61, s61, 0
	s_cmp_gt_u32 s56, 5
	s_cbranch_scc0 .LBB0_700
	s_and_b64 vcc, exec, s[14:15]
	s_cbranch_vccz .LBB0_703
	s_barrier

; #define PG8_STAGE(bufoff, gbase, voff) do { _Pragma("unroll") for (int _i = 0; _i < 2; ++_i) \
;         __builtin_amdgcn_global_load_lds((const unsigned*)((const char*)(gbase) + (voff)[_i]), (PG8_LAS unsigned*)(lds + (bufoff) + ldsw + _i * 8192), 16, 0, 0); } while (0)
; #define PG8_LDA(dst, b, h) do { _Pragma("unroll") for (int m = 0; m < 4; ++m) _Pragma("unroll") for (int k = 0; k < 2; ++k) dst[m][k] = *(const PG8_LAS bf16x8*)(lds + PG8_SA(b, h) + aoff + m * 2048 + k * 1024); } while (0)
; #define PG8_LDB(dst, b, h) do { _Pragma("unroll") for (int n = 0; n < 2; ++n) _Pragma("unroll") for (int k = 0; k < 2; ++k) dst[n][k] = *(const PG8_LAS bf16x8*)(lds + PG8_SB(b, h) + boff + n * 2048 + k * 1024); } while (0)
; #define PG8_MMA(ai, bj, At, Bt) do { __builtin_amdgcn_s_setprio(1); _Pragma("unroll") for (int m = 0; m < 4; ++m) _Pragma("unroll") for (int n = 0; n < 2; ++n) _Pragma("unroll") for (int k = 0; k < 2; ++k) \
;         acc[ai][bj][m][n] = __builtin_amdgcn_mfma_f32_16x16x32_bf16(Bt[n][k], At[m][k], acc[ai][bj][m][n], 0, 0, 0); __builtin_amdgcn_s_setprio(0); } while (0)
; #define PG8_WAIT_V(n) asm volatile("s_waitcnt vmcnt(" #n ")" ::: "memory")
; #define PG8_WAIT_L(n) asm volatile("s_waitcnt lgkmcnt(" #n ")" ::: "memory")
; template <class Epi, class Sched, bool ALIGN_EPI = false, bool SP2 = false>
; __device__ __forceinline__ void gemm_phase(PG8_LAS unsigned char* lds, const Gemm g, const Sched& S, const Epi& E) {
;     ...
;             const bool last = (t == nt - 2);
;             const char* a1 = cA + (size_t)(t + 1) * kstep;
;             const char* a2 = last ? nA : cA + (size_t)(t + 2) * kstep; const char* b2 = last ? nB : cB + (size_t)(t + 2) * kstep;
;             const char* a3 = a2 + kstep; const char* b3 = b2 + kstep;
;             if (last && has_next) S.a_ready(nxt);
;             if constexpr (SP2) {
;             PG8_LDB(B0, 0, 0); PG8_LDB(B1, 0, 1); PG8_SCHED; PG8_LDA(At, 0, 0); PG8_STAGE(PG8_SA(1, 1), a1 + hstep, voffA);
;             PG8_WAIT_V(8); PG8_WAIT_L(0); PG8_BAR; PG8_MMA(0, 0, At, B0); PG8_MMA(0, 1, At, B1); PG8_BAR; PG8_SCHED;
;             PG8_LDA(At, 0, 1); PG8_STAGE(PG8_SB(0, 0), b2, voffB); PG8_STAGE(PG8_SB(0, 1), b2 + hstep, voffB); PG8_STAGE(PG8_SA(0, 0), a2, voffA);
;             PG8_WAIT_V(8); PG8_WAIT_L(0); PG8_BAR; PG8_MMA(1, 0, At, B0); PG8_MMA(1, 1, At, B1); PG8_BAR; PG8_SCHED;
.LBB0_770:
	s_add_u32 s65, s66, 0xfffc0080
	s_addc_u32 s68, s67, -1
	s_add_i32 s72, 0, 0x10000
	s_cmp_eq_u32 s63, 12
	s_cselect_b32 s71, s27, s68
	s_cselect_b32 s70, s53, s65
	v_add_u32_e32 v146, s72, v148
	s_cselect_b32 s69, s25, s56
	s_cselect_b32 s68, s54, s55
	s_add_i32 s65, 0, 0x14000
	ds_read_b128 v[142:145], v146
	ds_read_b128 v[152:155], v146 offset:1024
	ds_read_b128 v[156:159], v146 offset:2048
	ds_read_b128 v[160:163], v146 offset:3072
	v_add_u32_e32 v146, s65, v148
	ds_read_b128 v[164:167], v146
	ds_read_b128 v[168:171], v146 offset:1024
	ds_read_b128 v[172:175], v146 offset:2048
	ds_read_b128 v[180:183], v146 offset:3072
	s_add_i32 m0, s29, 0xc000
	ds_read_b128 v[184:187], v150
	ds_read_b128 v[200:203], v150 offset:1024
	ds_read_b128 v[204:207], v150 offset:2048
	ds_read_b128 v[208:211], v150 offset:3072
	ds_read_b128 v[212:215], v150 offset:4096
	ds_read_b128 v[216:219], v150 offset:5120
	ds_read_b128 v[220:223], v150 offset:6144
	ds_read_b128 v[224:227], v150 offset:7168
	global_load_lds_dwordx4 v140, s[66:67]
	s_add_i32 m0, s29, 0xe000
	s_nop 0
	global_load_lds_dwordx4 v138, s[66:67]
	s_waitcnt vmcnt(8)
	s_waitcnt lgkmcnt(0)
	s_barrier
	s_setprio 1
	v_mfma_f32_16x16x32_bf16 v[130:133], v[142:145], v[184:187], v[130:133]
	v_mfma_f32_16x16x32_bf16 v[126:129], v[156:159], v[184:187], v[126:129]
	v_mfma_f32_16x16x32_bf16 v[114:117], v[142:145], v[204:207], v[114:117]
	v_mfma_f32_16x16x32_bf16 v[110:113], v[156:159], v[204:207], v[110:113]
	v_mfma_f32_16x16x32_bf16 v[98:101], v[142:145], v[212:215], v[98:101]
	v_mfma_f32_16x16x32_bf16 v[94:97], v[156:159], v[212:215], v[94:97]
	v_mfma_f32_16x16x32_bf16 v[78:81], v[142:145], v[220:223], v[78:81]
	v_mfma_f32_16x16x32_bf16 v[74:77], v[156:159], v[220:223], v[74:77]
	v_mfma_f32_16x16x32_bf16 v[130:133], v[152:155], v[200:203], v[130:133]
	v_mfma_f32_16x16x32_bf16 v[126:129], v[160:163], v[200:203], v[126:129]
	v_mfma_f32_16x16x32_bf16 v[114:117], v[152:155], v[208:211], v[114:117]
	v_mfma_f32_16x16x32_bf16 v[110:113], v[160:163], v[208:211], v[110:113]
	v_mfma_f32_16x16x32_bf16 v[98:101], v[152:155], v[216:219], v[98:101]
	v_mfma_f32_16x16x32_bf16 v[94:97], v[160:163], v[216:219], v[94:97]
	v_mfma_f32_16x16x32_bf16 v[78:81], v[152:155], v[224:227], v[78:81]
	v_mfma_f32_16x16x32_bf16 v[74:77], v[160:163], v[224:227], v[74:77]
	v_mfma_f32_16x16x32_bf16 v[122:125], v[164:167], v[184:187], v[122:125]
	v_mfma_f32_16x16x32_bf16 v[118:121], v[172:175], v[184:187], v[118:121]
	v_mfma_f32_16x16x32_bf16 v[106:109], v[164:167], v[204:207], v[106:109]
	v_mfma_f32_16x16x32_bf16 v[102:105], v[172:175], v[204:207], v[102:105]
	v_mfma_f32_16x16x32_bf16 v[90:93], v[164:167], v[212:215], v[90:93]
	v_mfma_f32_16x16x32_bf16 v[86:89], v[172:175], v[212:215], v[86:89]
	v_mfma_f32_16x16x32_bf16 v[70:73], v[164:167], v[220:223], v[70:73]
	v_mfma_f32_16x16x32_bf16 v[66:69], v[172:175], v[220:223], v[66:69]
	v_mfma_f32_16x16x32_bf16 v[122:125], v[168:171], v[200:203], v[122:125]
	v_mfma_f32_16x16x32_bf16 v[118:121], v[180:183], v[200:203], v[118:121]
	v_mfma_f32_16x16x32_bf16 v[106:109], v[168:171], v[208:211], v[106:109]
	v_mfma_f32_16x16x32_bf16 v[102:105], v[180:183], v[208:211], v[102:105]
	v_mfma_f32_16x16x32_bf16 v[90:93], v[168:171], v[216:219], v[90:93]
	v_mfma_f32_16x16x32_bf16 v[86:89], v[180:183], v[216:219], v[86:89]
	v_mfma_f32_16x16x32_bf16 v[70:73], v[168:171], v[224:227], v[70:73]
	v_mfma_f32_16x16x32_bf16 v[66:69], v[180:183], v[224:227], v[66:69]
	s_setprio 0
	s_barrier
	s_add_i32 s72, s72, s28
	v_lshl_add_u64 v[146:147], s[68:69], 0, v[134:135]
	s_mov_b32 m0, s72
	ds_read_b128 v[184:187], v150 offset:16384
	ds_read_b128 v[200:203], v150 offset:17408
	ds_read_b128 v[204:207], v150 offset:18432
	ds_read_b128 v[208:211], v150 offset:19456
	ds_read_b128 v[212:215], v150 offset:20480
	ds_read_b128 v[216:219], v150 offset:21504
	ds_read_b128 v[220:223], v150 offset:22528
	ds_read_b128 v[224:227], v150 offset:23552
	global_load_lds_dwordx4 v[146:147], off
	s_add_i32 m0, s72, 0x2000
	s_add_u32 s72, s68, 0x40000
	v_lshl_add_u64 v[176:177], s[68:69], 0, v[136:137]
	s_addc_u32 s73, s69, 0
	s_add_i32 s65, s65, s28
	global_load_lds_dwordx4 v[176:177], off
	s_mov_b32 m0, s65
	v_lshl_add_u64 v[230:231], s[70:71], 0, v[136:137]
	global_load_lds_dwordx4 v134, s[72:73]
	s_add_i32 m0, s65, 0x2000
	s_nop 0
	global_load_lds_dwordx4 v136, s[72:73]
	v_lshl_add_u64 v[228:229], s[70:71], 0, v[134:135]
	s_mov_b32 m0, s29
	s_nop 0
	global_load_lds_dwordx4 v[228:229], off
	s_mov_b32 m0, s34
	s_nop 0
	global_load_lds_dwordx4 v[230:231], off
	s_waitcnt vmcnt(8)
	s_waitcnt lgkmcnt(0)
	s_barrier
; #define PG8_STAGE(bufoff, gbase, voff) do { _Pragma("unroll") for (int _i = 0; _i < 2; ++_i) \
;         __builtin_amdgcn_global_load_lds((const unsigned*)((const char*)(gbase) + (voff)[_i]), (PG8_LAS unsigned*)(lds + (bufoff) + ldsw + _i * 8192), 16, 0, 0); } while (0)
; #define PG8_LDA(dst, b, h) do { _Pragma("unroll") for (int m = 0; m < 4; ++m) _Pragma("unroll") for (int k = 0; k < 2; ++k) dst[m][k] = *(const PG8_LAS bf16x8*)(lds + PG8_SA(b, h) + aoff + m * 2048 + k * 1024); } while (0)
; #define PG8_LDB(dst, b, h) do { _Pragma("unroll") for (int n = 0; n < 2; ++n) _Pragma("unroll") for (int k = 0; k < 2; ++k) dst[n][k] = *(const PG8_LAS bf16x8*)(lds + PG8_SB(b, h) + boff + n * 2048 + k * 1024); } while (0)
; #define PG8_MMA(ai, bj, At, Bt) do { __builtin_amdgcn_s_setprio(1); _Pragma("unroll") for (int m = 0; m < 4; ++m) _Pragma("unroll") for (int n = 0; n < 2; ++n) _Pragma("unroll") for (int k = 0; k < 2; ++k) \
;         acc[ai][bj][m][n] = __builtin_amdgcn_mfma_f32_16x16x32_bf16(Bt[n][k], At[m][k], acc[ai][bj][m][n], 0, 0, 0); __builtin_amdgcn_s_setprio(0); } while (0)
; #define PG8_WAIT_V(n) asm volatile("s_waitcnt vmcnt(" #n ")" ::: "memory")
; #define PG8_WAIT_L(n) asm volatile("s_waitcnt lgkmcnt(" #n ")" ::: "memory")
; #define PG8_BAR __builtin_amdgcn_s_barrier()
; #define PG8_SCHED __builtin_amdgcn_sched_barrier(0)
; template <class Epi, class Sched, bool ALIGN_EPI = false, bool SP2 = false>
; __device__ __forceinline__ void gemm_phase(PG8_LAS unsigned char* lds, const Gemm g, const Sched& S, const Epi& E) {
;     ...
;             PG8_WAIT_V(8); PG8_WAIT_L(0); PG8_BAR; PG8_MMA(1, 0, At, B0); PG8_MMA(1, 1, At, B1); PG8_BAR; PG8_SCHED;
;             PG8_LDB(B0, 1, 0); PG8_LDB(B1, 1, 1); PG8_SCHED; PG8_LDA(At, 1, 0); PG8_STAGE(PG8_SA(0, 1), a2 + hstep, voffA);
;             PG8_WAIT_V(8); PG8_WAIT_L(0); PG8_BAR; PG8_MMA(0, 0, At, B0); PG8_MMA(0, 1, At, B1); PG8_BAR; PG8_SCHED;
	s_setprio 1
	v_mfma_f32_16x16x32_bf16 v[62:65], v[142:145], v[184:187], v[62:65]
	v_mfma_f32_16x16x32_bf16 v[58:61], v[156:159], v[184:187], v[58:61]
	v_mfma_f32_16x16x32_bf16 v[46:49], v[142:145], v[204:207], v[46:49]
	v_mfma_f32_16x16x32_bf16 v[42:45], v[156:159], v[204:207], v[42:45]
	v_mfma_f32_16x16x32_bf16 v[30:33], v[142:145], v[212:215], v[30:33]
	v_mfma_f32_16x16x32_bf16 v[26:29], v[156:159], v[212:215], v[26:29]
	v_mfma_f32_16x16x32_bf16 v[14:17], v[142:145], v[220:223], v[14:17]
	v_mfma_f32_16x16x32_bf16 v[10:13], v[156:159], v[220:223], v[10:13]
	v_mfma_f32_16x16x32_bf16 v[62:65], v[152:155], v[200:203], v[62:65]
	v_mfma_f32_16x16x32_bf16 v[58:61], v[160:163], v[200:203], v[58:61]
	v_mfma_f32_16x16x32_bf16 v[46:49], v[152:155], v[208:211], v[46:49]
	v_mfma_f32_16x16x32_bf16 v[42:45], v[160:163], v[208:211], v[42:45]
	v_mfma_f32_16x16x32_bf16 v[30:33], v[152:155], v[216:219], v[30:33]
	v_mfma_f32_16x16x32_bf16 v[26:29], v[160:163], v[216:219], v[26:29]
	v_mfma_f32_16x16x32_bf16 v[14:17], v[152:155], v[224:227], v[14:17]
	v_mfma_f32_16x16x32_bf16 v[10:13], v[160:163], v[224:227], v[10:13]
	v_mfma_f32_16x16x32_bf16 v[54:57], v[164:167], v[184:187], v[54:57]
	v_mfma_f32_16x16x32_bf16 v[50:53], v[172:175], v[184:187], v[50:53]
	v_mfma_f32_16x16x32_bf16 v[38:41], v[164:167], v[204:207], v[38:41]
	v_mfma_f32_16x16x32_bf16 v[34:37], v[172:175], v[204:207], v[34:37]
	v_mfma_f32_16x16x32_bf16 v[22:25], v[164:167], v[212:215], v[22:25]
	v_mfma_f32_16x16x32_bf16 v[18:21], v[172:175], v[212:215], v[18:21]
	v_mfma_f32_16x16x32_bf16 v[6:9], v[164:167], v[220:223], v[6:9]
	v_mfma_f32_16x16x32_bf16 v[2:5], v[172:175], v[220:223], v[2:5]
	v_mfma_f32_16x16x32_bf16 v[54:57], v[168:171], v[200:203], v[54:57]
	v_mfma_f32_16x16x32_bf16 v[50:53], v[180:183], v[200:203], v[50:53]
	v_mfma_f32_16x16x32_bf16 v[38:41], v[168:171], v[208:211], v[38:41]
	v_mfma_f32_16x16x32_bf16 v[34:37], v[180:183], v[208:211], v[34:37]
	v_mfma_f32_16x16x32_bf16 v[22:25], v[168:171], v[216:219], v[22:25]
	v_mfma_f32_16x16x32_bf16 v[18:21], v[180:183], v[216:219], v[18:21]
	v_mfma_f32_16x16x32_bf16 v[6:9], v[168:171], v[224:227], v[6:9]
	v_mfma_f32_16x16x32_bf16 v[2:5], v[180:183], v[224:227], v[2:5]
	s_setprio 0
	s_barrier
	s_add_i32 s65, 0, 0x18000
	v_add_u32_e32 v151, s65, v148
	s_add_i32 s72, 0, 0x1c000
	ds_read_b128 v[142:145], v151
	ds_read_b128 v[152:155], v151 offset:1024
	ds_read_b128 v[156:159], v151 offset:2048
	ds_read_b128 v[160:163], v151 offset:3072
	v_add_u32_e32 v151, s72, v148
	ds_read_b128 v[164:167], v151
	ds_read_b128 v[168:171], v151 offset:1024
	ds_read_b128 v[172:175], v151 offset:2048
	ds_read_b128 v[180:183], v151 offset:3072
	s_add_u32 s70, s70, 0x40000
	s_addc_u32 s71, s71, 0
	s_mov_b32 m0, s36
	ds_read_b128 v[184:187], v150 offset:32768
	ds_read_b128 v[200:203], v150 offset:33792
	ds_read_b128 v[204:207], v150 offset:34816
	ds_read_b128 v[208:211], v150 offset:35840
	ds_read_b128 v[212:215], v150 offset:36864
	ds_read_b128 v[216:219], v150 offset:37888
	ds_read_b128 v[220:223], v150 offset:38912
	ds_read_b128 v[224:227], v150 offset:39936
	global_load_lds_dwordx4 v134, s[70:71]
	s_mov_b32 m0, s37
	s_nop 0
	global_load_lds_dwordx4 v136, s[70:71]
	s_waitcnt vmcnt(8)
	s_waitcnt lgkmcnt(0)
	s_barrier
	s_setprio 1
	v_mfma_f32_16x16x32_bf16 v[130:133], v[142:145], v[184:187], v[130:133]
	v_mfma_f32_16x16x32_bf16 v[126:129], v[156:159], v[184:187], v[126:129]
	v_mfma_f32_16x16x32_bf16 v[114:117], v[142:145], v[204:207], v[114:117]
	v_mfma_f32_16x16x32_bf16 v[110:113], v[156:159], v[204:207], v[110:113]
	v_mfma_f32_16x16x32_bf16 v[98:101], v[142:145], v[212:215], v[98:101]
	v_mfma_f32_16x16x32_bf16 v[94:97], v[156:159], v[212:215], v[94:97]
	v_mfma_f32_16x16x32_bf16 v[78:81], v[142:145], v[220:223], v[78:81]
	v_mfma_f32_16x16x32_bf16 v[74:77], v[156:159], v[220:223], v[74:77]
	v_mfma_f32_16x16x32_bf16 v[130:133], v[152:155], v[200:203], v[130:133]
	v_mfma_f32_16x16x32_bf16 v[126:129], v[160:163], v[200:203], v[126:129]
	v_mfma_f32_16x16x32_bf16 v[114:117], v[152:155], v[208:211], v[114:117]
	v_mfma_f32_16x16x32_bf16 v[110:113], v[160:163], v[208:211], v[110:113]
	v_mfma_f32_16x16x32_bf16 v[98:101], v[152:155], v[216:219], v[98:101]
	v_mfma_f32_16x16x32_bf16 v[94:97], v[160:163], v[216:219], v[94:97]
	v_mfma_f32_16x16x32_bf16 v[78:81], v[152:155], v[224:227], v[78:81]
	v_mfma_f32_16x16x32_bf16 v[74:77], v[160:163], v[224:227], v[74:77]
	v_mfma_f32_16x16x32_bf16 v[122:125], v[164:167], v[184:187], v[122:125]
	v_mfma_f32_16x16x32_bf16 v[118:121], v[172:175], v[184:187], v[118:121]
	v_mfma_f32_16x16x32_bf16 v[106:109], v[164:167], v[204:207], v[106:109]
	v_mfma_f32_16x16x32_bf16 v[102:105], v[172:175], v[204:207], v[102:105]
	v_mfma_f32_16x16x32_bf16 v[90:93], v[164:167], v[212:215], v[90:93]
	v_mfma_f32_16x16x32_bf16 v[86:89], v[172:175], v[212:215], v[86:89]
	v_mfma_f32_16x16x32_bf16 v[70:73], v[164:167], v[220:223], v[70:73]
	v_mfma_f32_16x16x32_bf16 v[66:69], v[172:175], v[220:223], v[66:69]
	v_mfma_f32_16x16x32_bf16 v[122:125], v[168:171], v[200:203], v[122:125]
	v_mfma_f32_16x16x32_bf16 v[118:121], v[180:183], v[200:203], v[118:121]
	v_mfma_f32_16x16x32_bf16 v[106:109], v[168:171], v[208:211], v[106:109]
	v_mfma_f32_16x16x32_bf16 v[102:105], v[180:183], v[208:211], v[102:105]
	v_mfma_f32_16x16x32_bf16 v[90:93], v[168:171], v[216:219], v[90:93]
	v_mfma_f32_16x16x32_bf16 v[86:89], v[180:183], v[216:219], v[86:89]
	v_mfma_f32_16x16x32_bf16 v[70:73], v[168:171], v[224:227], v[70:73]
	v_mfma_f32_16x16x32_bf16 v[66:69], v[180:183], v[224:227], v[66:69]
	s_setprio 0
	s_barrier
; #define PG8_STAGE(bufoff, gbase, voff) do { _Pragma("unroll") for (int _i = 0; _i < 2; ++_i) \
;         __builtin_amdgcn_global_load_lds((const unsigned*)((const char*)(gbase) + (voff)[_i]), (PG8_LAS unsigned*)(lds + (bufoff) + ldsw + _i * 8192), 16, 0, 0); } while (0)
; #define PG8_LDA(dst, b, h) do { _Pragma("unroll") for (int m = 0; m < 4; ++m) _Pragma("unroll") for (int k = 0; k < 2; ++k) dst[m][k] = *(const PG8_LAS bf16x8*)(lds + PG8_SA(b, h) + aoff + m * 2048 + k * 1024); } while (0)
; #define PG8_MMA(ai, bj, At, Bt) do { __builtin_amdgcn_s_setprio(1); _Pragma("unroll") for (int m = 0; m < 4; ++m) _Pragma("unroll") for (int n = 0; n < 2; ++n) _Pragma("unroll") for (int k = 0; k < 2; ++k) \
;         acc[ai][bj][m][n] = __builtin_amdgcn_mfma_f32_16x16x32_bf16(Bt[n][k], At[m][k], acc[ai][bj][m][n], 0, 0, 0); __builtin_amdgcn_s_setprio(0); } while (0)
; #define PG8_WAIT_V(n) asm volatile("s_waitcnt vmcnt(" #n ")" ::: "memory")
; #define PG8_WAIT_L(n) asm volatile("s_waitcnt lgkmcnt(" #n ")" ::: "memory")
; #define PG8_BAR __builtin_amdgcn_s_barrier()
; #define PG8_SCHED __builtin_amdgcn_sched_barrier(0)
; template <class Epi, class Sched, bool ALIGN_EPI = false, bool SP2 = false>
; __device__ __forceinline__ void gemm_phase(PG8_LAS unsigned char* lds, const Gemm g, const Sched& S, const Epi& E) {
;     ...
;         for (int t = 0; t < nt; t += 2) {
;             const bool last = (t == nt - 2);
;             const char* a1 = cA + (size_t)(t + 1) * kstep;
;             const char* a2 = last ? nA : cA + (size_t)(t + 2) * kstep; const char* b2 = last ? nB : cB + (size_t)(t + 2) * kstep;
;             const char* a3 = a2 + kstep; const char* b3 = b2 + kstep;
;             if (last && has_next) S.a_ready(nxt);
;     ...
;             PG8_LDA(At, 1, 1); PG8_STAGE(PG8_SB(1, 0), b3, voffB); PG8_STAGE(PG8_SB(1, 1), b3 + hstep, voffB); PG8_STAGE(PG8_SA(1, 0), a3, voffA);
;             PG8_WAIT_V(8); PG8_WAIT_L(0); PG8_BAR; PG8_MMA(1, 0, At, B0); PG8_MMA(1, 1, At, B1); PG8_BAR; PG8_SCHED;
	s_add_i32 s65, s65, s28
	v_lshl_add_u64 v[146:147], v[146:147], 0, s[38:39]
	s_mov_b32 m0, s65
	ds_read_b128 v[184:187], v150 offset:49152
	ds_read_b128 v[200:203], v150 offset:50176
	ds_read_b128 v[204:207], v150 offset:51200
	ds_read_b128 v[208:211], v150 offset:52224
	ds_read_b128 v[212:215], v150 offset:53248
	ds_read_b128 v[216:219], v150 offset:54272
	ds_read_b128 v[220:223], v150 offset:55296
	ds_read_b128 v[224:227], v150 offset:56320
	global_load_lds_dwordx4 v[146:147], off
	s_add_i32 m0, s65, 0x2000
	s_add_u32 s68, s68, 0x40080
	v_lshl_add_u64 v[146:147], v[176:177], 0, s[38:39]
	s_addc_u32 s69, s69, 0
	s_add_i32 s65, s72, s28
	global_load_lds_dwordx4 v[146:147], off
	s_mov_b32 m0, s65
	s_nop 0
	global_load_lds_dwordx4 v134, s[68:69]
	s_add_i32 m0, s65, 0x2000
	s_nop 0
	global_load_lds_dwordx4 v136, s[68:69]
	v_lshl_add_u64 v[146:147], v[228:229], 0, s[38:39]
	s_mov_b32 m0, s41
	s_nop 0
	global_load_lds_dwordx4 v[146:147], off
	v_lshl_add_u64 v[146:147], v[230:231], 0, s[38:39]
	s_mov_b32 m0, s42
	s_nop 0
	global_load_lds_dwordx4 v[146:147], off
	s_waitcnt vmcnt(8)
	s_waitcnt lgkmcnt(0)
	s_barrier
	s_setprio 1
	v_mfma_f32_16x16x32_bf16 v[62:65], v[142:145], v[184:187], v[62:65]
	v_mfma_f32_16x16x32_bf16 v[58:61], v[156:159], v[184:187], v[58:61]
	v_mfma_f32_16x16x32_bf16 v[46:49], v[142:145], v[204:207], v[46:49]
	v_mfma_f32_16x16x32_bf16 v[42:45], v[156:159], v[204:207], v[42:45]
	v_mfma_f32_16x16x32_bf16 v[30:33], v[142:145], v[212:215], v[30:33]
	v_mfma_f32_16x16x32_bf16 v[26:29], v[156:159], v[212:215], v[26:29]
	v_mfma_f32_16x16x32_bf16 v[14:17], v[142:145], v[220:223], v[14:17]
	v_mfma_f32_16x16x32_bf16 v[10:13], v[156:159], v[220:223], v[10:13]
	v_mfma_f32_16x16x32_bf16 v[62:65], v[152:155], v[200:203], v[62:65]
	v_mfma_f32_16x16x32_bf16 v[58:61], v[160:163], v[200:203], v[58:61]
	v_mfma_f32_16x16x32_bf16 v[46:49], v[152:155], v[208:211], v[46:49]
	v_mfma_f32_16x16x32_bf16 v[42:45], v[160:163], v[208:211], v[42:45]
	v_mfma_f32_16x16x32_bf16 v[30:33], v[152:155], v[216:219], v[30:33]
	v_mfma_f32_16x16x32_bf16 v[26:29], v[160:163], v[216:219], v[26:29]
	v_mfma_f32_16x16x32_bf16 v[14:17], v[152:155], v[224:227], v[14:17]
	v_mfma_f32_16x16x32_bf16 v[10:13], v[160:163], v[224:227], v[10:13]
	v_mfma_f32_16x16x32_bf16 v[54:57], v[164:167], v[184:187], v[54:57]
	v_mfma_f32_16x16x32_bf16 v[50:53], v[172:175], v[184:187], v[50:53]
	v_mfma_f32_16x16x32_bf16 v[38:41], v[164:167], v[204:207], v[38:41]
	v_mfma_f32_16x16x32_bf16 v[34:37], v[172:175], v[204:207], v[34:37]
	v_mfma_f32_16x16x32_bf16 v[22:25], v[164:167], v[212:215], v[22:25]
	v_mfma_f32_16x16x32_bf16 v[18:21], v[172:175], v[212:215], v[18:21]
	v_mfma_f32_16x16x32_bf16 v[6:9], v[164:167], v[220:223], v[6:9]
	v_mfma_f32_16x16x32_bf16 v[2:5], v[172:175], v[220:223], v[2:5]
	v_mfma_f32_16x16x32_bf16 v[54:57], v[168:171], v[200:203], v[54:57]
	v_mfma_f32_16x16x32_bf16 v[50:53], v[180:183], v[200:203], v[50:53]
	v_mfma_f32_16x16x32_bf16 v[38:41], v[168:171], v[208:211], v[38:41]
	v_mfma_f32_16x16x32_bf16 v[34:37], v[180:183], v[208:211], v[34:37]
	v_mfma_f32_16x16x32_bf16 v[22:25], v[168:171], v[216:219], v[22:25]
	v_mfma_f32_16x16x32_bf16 v[18:21], v[180:183], v[216:219], v[18:21]
	v_mfma_f32_16x16x32_bf16 v[6:9], v[168:171], v[224:227], v[6:9]
	v_mfma_f32_16x16x32_bf16 v[2:5], v[180:183], v[224:227], v[2:5]
	s_setprio 0
	s_barrier
	s_add_i32 s63, s63, 2
	s_add_u32 s55, s55, 0x100
	s_addc_u32 s56, s56, 0
	s_add_u32 s66, s66, 0x100
	s_addc_u32 s67, s67, 0
	s_cmp_gt_u32 s63, 13
	s_cbranch_scc0 .LBB0_770
	s_and_b64 vcc, exec, s[20:21]
	s_cbranch_vccz .LBB0_773
	s_barrier

; #define PG8_STAGE(bufoff, gbase, voff) do { _Pragma("unroll") for (int _i = 0; _i < 2; ++_i) \
;         __builtin_amdgcn_global_load_lds((const unsigned*)((const char*)(gbase) + (voff)[_i]), (PG8_LAS unsigned*)(lds + (bufoff) + ldsw + _i * 8192), 16, 0, 0); } while (0)
; #define PG8_LDA(dst, b, h) do { _Pragma("unroll") for (int m = 0; m < 4; ++m) _Pragma("unroll") for (int k = 0; k < 2; ++k) dst[m][k] = *(const PG8_LAS bf16x8*)(lds + PG8_SA(b, h) + aoff + m * 2048 + k * 1024); } while (0)
; #define PG8_LDB(dst, b, h) do { _Pragma("unroll") for (int n = 0; n < 2; ++n) _Pragma("unroll") for (int k = 0; k < 2; ++k) dst[n][k] = *(const PG8_LAS bf16x8*)(lds + PG8_SB(b, h) + boff + n * 2048 + k * 1024); } while (0)
; #define PG8_MMA(ai, bj, At, Bt) do { __builtin_amdgcn_s_setprio(1); _Pragma("unroll") for (int m = 0; m < 4; ++m) _Pragma("unroll") for (int n = 0; n < 2; ++n) _Pragma("unroll") for (int k = 0; k < 2; ++k) \
;         acc[ai][bj][m][n] = __builtin_amdgcn_mfma_f32_16x16x32_bf16(Bt[n][k], At[m][k], acc[ai][bj][m][n], 0, 0, 0); __builtin_amdgcn_s_setprio(0); } while (0)
; #define PG8_WAIT_V(n) asm volatile("s_waitcnt vmcnt(" #n ")" ::: "memory")
; #define PG8_WAIT_L(n) asm volatile("s_waitcnt lgkmcnt(" #n ")" ::: "memory")
; template <class Epi, class Sched, bool ALIGN_EPI = false, bool SP2 = false>
; __device__ __forceinline__ void gemm_phase(PG8_LAS unsigned char* lds, const Gemm g, const Sched& S, const Epi& E) {
;     ...
;             const bool last = (t == nt - 2);
;             const char* a1 = cA + (size_t)(t + 1) * kstep;
;             const char* a2 = last ? nA : cA + (size_t)(t + 2) * kstep; const char* b2 = last ? nB : cB + (size_t)(t + 2) * kstep;
;             const char* a3 = a2 + kstep; const char* b3 = b2 + kstep;
;             if (last && has_next) S.a_ready(nxt);
;             if constexpr (SP2) {
;             PG8_LDB(B0, 0, 0); PG8_LDB(B1, 0, 1); PG8_SCHED; PG8_LDA(At, 0, 0); PG8_STAGE(PG8_SA(1, 1), a1 + hstep, voffA);
;             PG8_WAIT_V(8); PG8_WAIT_L(0); PG8_BAR; PG8_MMA(0, 0, At, B0); PG8_MMA(0, 1, At, B1); PG8_BAR; PG8_SCHED;
;             PG8_LDA(At, 0, 1); PG8_STAGE(PG8_SB(0, 0), b2, voffB); PG8_STAGE(PG8_SB(0, 1), b2 + hstep, voffB); PG8_STAGE(PG8_SA(0, 0), a2, voffA);
;             PG8_WAIT_V(8); PG8_WAIT_L(0); PG8_BAR; PG8_MMA(1, 0, At, B0); PG8_MMA(1, 1, At, B1); PG8_BAR; PG8_SCHED;
.LBB0_856:
	s_add_u32 s78, s76, 0xfffc0080
	s_addc_u32 s79, s77, -1
	s_add_i32 s84, 0, 0x10000
	s_cmp_eq_u32 s83, 12
	s_cselect_b32 s81, s56, s79
	s_cselect_b32 s80, s67, s78
	s_cselect_b32 s79, s65, s82
	s_cselect_b32 s78, s73, s75
	s_add_i32 s86, 0, 0x14000
	v_add_u32_e32 v146, s84, v177
	v_add_u32_e32 v174, s86, v177
	ds_read_b128 v[134:137], v146
	ds_read_b128 v[138:141], v146 offset:1024
	ds_read_b128 v[142:145], v146 offset:2048
	ds_read_b128 v[146:149], v146 offset:3072
	ds_read_b128 v[162:165], v174
	ds_read_b128 v[166:169], v174 offset:1024
	ds_read_b128 v[170:173], v174 offset:2048
	ds_read_b128 v[182:185], v174 offset:3072
	s_add_i32 m0, s36, 0xc000
	ds_read_b128 v[200:203], v180
	ds_read_b128 v[204:207], v180 offset:1024
	ds_read_b128 v[208:211], v180 offset:2048
	ds_read_b128 v[212:215], v180 offset:3072
	ds_read_b128 v[216:219], v180 offset:4096
	ds_read_b128 v[220:223], v180 offset:5120
	ds_read_b128 v[224:227], v180 offset:6144
	ds_read_b128 v[228:231], v180 offset:7168
	global_load_lds_dwordx4 v160, s[76:77]
	s_add_i32 m0, s36, 0xe000
	s_nop 0
	global_load_lds_dwordx4 v158, s[76:77]
	s_waitcnt vmcnt(8)
	s_waitcnt lgkmcnt(0)
	s_barrier
	s_setprio 1
	v_mfma_f32_16x16x32_bf16 v[130:133], v[134:137], v[200:203], v[130:133]
	v_mfma_f32_16x16x32_bf16 v[102:105], v[142:145], v[200:203], v[102:105]
	v_mfma_f32_16x16x32_bf16 v[126:129], v[134:137], v[208:211], v[126:129]
	v_mfma_f32_16x16x32_bf16 v[98:101], v[142:145], v[208:211], v[98:101]
	v_mfma_f32_16x16x32_bf16 v[122:125], v[134:137], v[216:219], v[122:125]
	v_mfma_f32_16x16x32_bf16 v[90:93], v[142:145], v[216:219], v[90:93]
	v_mfma_f32_16x16x32_bf16 v[118:121], v[134:137], v[224:227], v[118:121]
	v_mfma_f32_16x16x32_bf16 v[86:89], v[142:145], v[224:227], v[86:89]
	v_mfma_f32_16x16x32_bf16 v[130:133], v[138:141], v[204:207], v[130:133]
	v_mfma_f32_16x16x32_bf16 v[102:105], v[146:149], v[204:207], v[102:105]
	v_mfma_f32_16x16x32_bf16 v[126:129], v[138:141], v[212:215], v[126:129]
	v_mfma_f32_16x16x32_bf16 v[98:101], v[146:149], v[212:215], v[98:101]
	v_mfma_f32_16x16x32_bf16 v[122:125], v[138:141], v[220:223], v[122:125]
	v_mfma_f32_16x16x32_bf16 v[90:93], v[146:149], v[220:223], v[90:93]
	v_mfma_f32_16x16x32_bf16 v[118:121], v[138:141], v[228:231], v[118:121]
	v_mfma_f32_16x16x32_bf16 v[86:89], v[146:149], v[228:231], v[86:89]
	v_mfma_f32_16x16x32_bf16 v[94:97], v[162:165], v[200:203], v[94:97]
	v_mfma_f32_16x16x32_bf16 v[66:69], v[170:173], v[200:203], v[66:69]
	v_mfma_f32_16x16x32_bf16 v[114:117], v[162:165], v[208:211], v[114:117]
	v_mfma_f32_16x16x32_bf16 v[78:81], v[170:173], v[208:211], v[78:81]
	v_mfma_f32_16x16x32_bf16 v[110:113], v[162:165], v[216:219], v[110:113]
	v_mfma_f32_16x16x32_bf16 v[74:77], v[170:173], v[216:219], v[74:77]
	v_mfma_f32_16x16x32_bf16 v[106:109], v[162:165], v[224:227], v[106:109]
	v_mfma_f32_16x16x32_bf16 v[70:73], v[170:173], v[224:227], v[70:73]
	v_mfma_f32_16x16x32_bf16 v[94:97], v[166:169], v[204:207], v[94:97]
	v_mfma_f32_16x16x32_bf16 v[66:69], v[182:185], v[204:207], v[66:69]
	v_mfma_f32_16x16x32_bf16 v[114:117], v[166:169], v[212:215], v[114:117]
	v_mfma_f32_16x16x32_bf16 v[78:81], v[182:185], v[212:215], v[78:81]
	v_mfma_f32_16x16x32_bf16 v[110:113], v[166:169], v[220:223], v[110:113]
	v_mfma_f32_16x16x32_bf16 v[74:77], v[182:185], v[220:223], v[74:77]
	v_mfma_f32_16x16x32_bf16 v[106:109], v[166:169], v[228:231], v[106:109]
	v_mfma_f32_16x16x32_bf16 v[70:73], v[182:185], v[228:231], v[70:73]
	s_setprio 0
	s_barrier
	s_add_i32 s84, s84, s34
	v_lshl_add_u64 v[174:175], s[78:79], 0, v[152:153]
	s_mov_b32 m0, s84
	ds_read_b128 v[200:203], v180 offset:16384
	ds_read_b128 v[204:207], v180 offset:17408
	ds_read_b128 v[208:211], v180 offset:18432
	ds_read_b128 v[212:215], v180 offset:19456
	ds_read_b128 v[216:219], v180 offset:20480
	ds_read_b128 v[220:223], v180 offset:21504
	ds_read_b128 v[224:227], v180 offset:22528
	ds_read_b128 v[228:231], v180 offset:23552
	global_load_lds_dwordx4 v[174:175], off
	s_add_i32 m0, s84, 0x2000
	s_add_u32 s84, s78, 0x40000
	v_lshl_add_u64 v[186:187], s[78:79], 0, v[156:157]
	s_addc_u32 s85, s79, 0
	s_add_i32 s86, s86, s34
	global_load_lds_dwordx4 v[186:187], off
	s_mov_b32 m0, s86
	v_lshl_add_u64 v[234:235], s[80:81], 0, v[154:155]
	global_load_lds_dwordx4 v152, s[84:85]
	s_add_i32 m0, s86, 0x2000
	s_nop 0
	global_load_lds_dwordx4 v156, s[84:85]
	v_lshl_add_u64 v[232:233], s[80:81], 0, v[150:151]
	s_mov_b32 m0, s36
	s_nop 0
	global_load_lds_dwordx4 v[232:233], off
	s_mov_b32 m0, s37
	s_nop 0
	global_load_lds_dwordx4 v[234:235], off
	s_waitcnt vmcnt(8)
	s_waitcnt lgkmcnt(0)
	s_barrier
; #define PG8_STAGE(bufoff, gbase, voff) do { _Pragma("unroll") for (int _i = 0; _i < 2; ++_i) \
;         __builtin_amdgcn_global_load_lds((const unsigned*)((const char*)(gbase) + (voff)[_i]), (PG8_LAS unsigned*)(lds + (bufoff) + ldsw + _i * 8192), 16, 0, 0); } while (0)
; #define PG8_LDA(dst, b, h) do { _Pragma("unroll") for (int m = 0; m < 4; ++m) _Pragma("unroll") for (int k = 0; k < 2; ++k) dst[m][k] = *(const PG8_LAS bf16x8*)(lds + PG8_SA(b, h) + aoff + m * 2048 + k * 1024); } while (0)
; #define PG8_LDB(dst, b, h) do { _Pragma("unroll") for (int n = 0; n < 2; ++n) _Pragma("unroll") for (int k = 0; k < 2; ++k) dst[n][k] = *(const PG8_LAS bf16x8*)(lds + PG8_SB(b, h) + boff + n * 2048 + k * 1024); } while (0)
; #define PG8_MMA(ai, bj, At, Bt) do { __builtin_amdgcn_s_setprio(1); _Pragma("unroll") for (int m = 0; m < 4; ++m) _Pragma("unroll") for (int n = 0; n < 2; ++n) _Pragma("unroll") for (int k = 0; k < 2; ++k) \
;         acc[ai][bj][m][n] = __builtin_amdgcn_mfma_f32_16x16x32_bf16(Bt[n][k], At[m][k], acc[ai][bj][m][n], 0, 0, 0); __builtin_amdgcn_s_setprio(0); } while (0)
; #define PG8_WAIT_V(n) asm volatile("s_waitcnt vmcnt(" #n ")" ::: "memory")
; #define PG8_WAIT_L(n) asm volatile("s_waitcnt lgkmcnt(" #n ")" ::: "memory")
; #define PG8_BAR __builtin_amdgcn_s_barrier()
; #define PG8_SCHED __builtin_amdgcn_sched_barrier(0)
; template <class Epi, class Sched, bool ALIGN_EPI = false, bool SP2 = false>
; __device__ __forceinline__ void gemm_phase(PG8_LAS unsigned char* lds, const Gemm g, const Sched& S, const Epi& E) {
;     ...
;             PG8_WAIT_V(8); PG8_WAIT_L(0); PG8_BAR; PG8_MMA(1, 0, At, B0); PG8_MMA(1, 1, At, B1); PG8_BAR; PG8_SCHED;
;             PG8_LDB(B0, 1, 0); PG8_LDB(B1, 1, 1); PG8_SCHED; PG8_LDA(At, 1, 0); PG8_STAGE(PG8_SA(0, 1), a2 + hstep, voffA);
;             PG8_WAIT_V(8); PG8_WAIT_L(0); PG8_BAR; PG8_MMA(0, 0, At, B0); PG8_MMA(0, 1, At, B1); PG8_BAR; PG8_SCHED;
	s_setprio 1
	v_mfma_f32_16x16x32_bf16 v[62:65], v[134:137], v[200:203], v[62:65]
	v_mfma_f32_16x16x32_bf16 v[30:33], v[142:145], v[200:203], v[30:33]
	v_mfma_f32_16x16x32_bf16 v[58:61], v[134:137], v[208:211], v[58:61]
	v_mfma_f32_16x16x32_bf16 v[26:29], v[142:145], v[208:211], v[26:29]
	v_mfma_f32_16x16x32_bf16 v[54:57], v[134:137], v[216:219], v[54:57]
	v_mfma_f32_16x16x32_bf16 v[22:25], v[142:145], v[216:219], v[22:25]
	v_mfma_f32_16x16x32_bf16 v[50:53], v[134:137], v[224:227], v[50:53]
	v_mfma_f32_16x16x32_bf16 v[18:21], v[142:145], v[224:227], v[18:21]
	v_mfma_f32_16x16x32_bf16 v[62:65], v[138:141], v[204:207], v[62:65]
	v_mfma_f32_16x16x32_bf16 v[30:33], v[146:149], v[204:207], v[30:33]
	v_mfma_f32_16x16x32_bf16 v[58:61], v[138:141], v[212:215], v[58:61]
	v_mfma_f32_16x16x32_bf16 v[26:29], v[146:149], v[212:215], v[26:29]
	v_mfma_f32_16x16x32_bf16 v[54:57], v[138:141], v[220:223], v[54:57]
	v_mfma_f32_16x16x32_bf16 v[22:25], v[146:149], v[220:223], v[22:25]
	v_mfma_f32_16x16x32_bf16 v[50:53], v[138:141], v[228:231], v[50:53]
	v_mfma_f32_16x16x32_bf16 v[18:21], v[146:149], v[228:231], v[18:21]
	v_mfma_f32_16x16x32_bf16 v[34:37], v[162:165], v[200:203], v[34:37]
	v_mfma_f32_16x16x32_bf16 v[2:5], v[170:173], v[200:203], v[2:5]
	v_mfma_f32_16x16x32_bf16 v[46:49], v[162:165], v[208:211], v[46:49]
	v_mfma_f32_16x16x32_bf16 v[14:17], v[170:173], v[208:211], v[14:17]
	v_mfma_f32_16x16x32_bf16 v[42:45], v[162:165], v[216:219], v[42:45]
	v_mfma_f32_16x16x32_bf16 v[10:13], v[170:173], v[216:219], v[10:13]
	v_mfma_f32_16x16x32_bf16 v[38:41], v[162:165], v[224:227], v[38:41]
	v_mfma_f32_16x16x32_bf16 v[6:9], v[170:173], v[224:227], v[6:9]
	v_mfma_f32_16x16x32_bf16 v[34:37], v[166:169], v[204:207], v[34:37]
	v_mfma_f32_16x16x32_bf16 v[2:5], v[182:185], v[204:207], v[2:5]
	v_mfma_f32_16x16x32_bf16 v[46:49], v[166:169], v[212:215], v[46:49]
	v_mfma_f32_16x16x32_bf16 v[14:17], v[182:185], v[212:215], v[14:17]
	v_mfma_f32_16x16x32_bf16 v[42:45], v[166:169], v[220:223], v[42:45]
	v_mfma_f32_16x16x32_bf16 v[10:13], v[182:185], v[220:223], v[10:13]
	v_mfma_f32_16x16x32_bf16 v[38:41], v[166:169], v[228:231], v[38:41]
	v_mfma_f32_16x16x32_bf16 v[6:9], v[182:185], v[228:231], v[6:9]
	s_setprio 0
	s_barrier
	s_add_i32 s84, 0, 0x18000
	s_add_i32 s85, 0, 0x1c000
	v_add_u32_e32 v146, s84, v177
	v_add_u32_e32 v181, s85, v177
	ds_read_b128 v[134:137], v146
	ds_read_b128 v[138:141], v146 offset:1024
	ds_read_b128 v[142:145], v146 offset:2048
	ds_read_b128 v[146:149], v146 offset:3072
	ds_read_b128 v[162:165], v181
	ds_read_b128 v[166:169], v181 offset:1024
	ds_read_b128 v[170:173], v181 offset:2048
	ds_read_b128 v[182:185], v181 offset:3072
	s_add_u32 s80, s80, 0x40000
	s_addc_u32 s81, s81, 0
	s_mov_b32 m0, s40
	ds_read_b128 v[200:203], v180 offset:32768
	ds_read_b128 v[204:207], v180 offset:33792
	ds_read_b128 v[208:211], v180 offset:34816
	ds_read_b128 v[212:215], v180 offset:35840
	ds_read_b128 v[216:219], v180 offset:36864
	ds_read_b128 v[220:223], v180 offset:37888
	ds_read_b128 v[224:227], v180 offset:38912
	ds_read_b128 v[228:231], v180 offset:39936
	global_load_lds_dwordx4 v150, s[80:81]
	s_mov_b32 m0, s41
	s_nop 0
	global_load_lds_dwordx4 v154, s[80:81]
	s_waitcnt vmcnt(8)
	s_waitcnt lgkmcnt(0)
	s_barrier
	s_setprio 1
	v_mfma_f32_16x16x32_bf16 v[130:133], v[134:137], v[200:203], v[130:133]
	v_mfma_f32_16x16x32_bf16 v[102:105], v[142:145], v[200:203], v[102:105]
	v_mfma_f32_16x16x32_bf16 v[126:129], v[134:137], v[208:211], v[126:129]
	v_mfma_f32_16x16x32_bf16 v[98:101], v[142:145], v[208:211], v[98:101]
	v_mfma_f32_16x16x32_bf16 v[122:125], v[134:137], v[216:219], v[122:125]
	v_mfma_f32_16x16x32_bf16 v[90:93], v[142:145], v[216:219], v[90:93]
	v_mfma_f32_16x16x32_bf16 v[118:121], v[134:137], v[224:227], v[118:121]
	v_mfma_f32_16x16x32_bf16 v[86:89], v[142:145], v[224:227], v[86:89]
	v_mfma_f32_16x16x32_bf16 v[130:133], v[138:141], v[204:207], v[130:133]
	v_mfma_f32_16x16x32_bf16 v[102:105], v[146:149], v[204:207], v[102:105]
	v_mfma_f32_16x16x32_bf16 v[126:129], v[138:141], v[212:215], v[126:129]
	v_mfma_f32_16x16x32_bf16 v[98:101], v[146:149], v[212:215], v[98:101]
	v_mfma_f32_16x16x32_bf16 v[122:125], v[138:141], v[220:223], v[122:125]
	v_mfma_f32_16x16x32_bf16 v[90:93], v[146:149], v[220:223], v[90:93]
	v_mfma_f32_16x16x32_bf16 v[118:121], v[138:141], v[228:231], v[118:121]
	v_mfma_f32_16x16x32_bf16 v[86:89], v[146:149], v[228:231], v[86:89]
	v_mfma_f32_16x16x32_bf16 v[94:97], v[162:165], v[200:203], v[94:97]
	v_mfma_f32_16x16x32_bf16 v[66:69], v[170:173], v[200:203], v[66:69]
	v_mfma_f32_16x16x32_bf16 v[114:117], v[162:165], v[208:211], v[114:117]
	v_mfma_f32_16x16x32_bf16 v[78:81], v[170:173], v[208:211], v[78:81]
	v_mfma_f32_16x16x32_bf16 v[110:113], v[162:165], v[216:219], v[110:113]
	v_mfma_f32_16x16x32_bf16 v[74:77], v[170:173], v[216:219], v[74:77]
	v_mfma_f32_16x16x32_bf16 v[106:109], v[162:165], v[224:227], v[106:109]
	v_mfma_f32_16x16x32_bf16 v[70:73], v[170:173], v[224:227], v[70:73]
	v_mfma_f32_16x16x32_bf16 v[94:97], v[166:169], v[204:207], v[94:97]
	v_mfma_f32_16x16x32_bf16 v[66:69], v[182:185], v[204:207], v[66:69]
	v_mfma_f32_16x16x32_bf16 v[114:117], v[166:169], v[212:215], v[114:117]
	v_mfma_f32_16x16x32_bf16 v[78:81], v[182:185], v[212:215], v[78:81]
	v_mfma_f32_16x16x32_bf16 v[110:113], v[166:169], v[220:223], v[110:113]
	v_mfma_f32_16x16x32_bf16 v[74:77], v[182:185], v[220:223], v[74:77]
	v_mfma_f32_16x16x32_bf16 v[106:109], v[166:169], v[228:231], v[106:109]
	v_mfma_f32_16x16x32_bf16 v[70:73], v[182:185], v[228:231], v[70:73]
	s_setprio 0
	s_barrier
; #define PG8_STAGE(bufoff, gbase, voff) do { _Pragma("unroll") for (int _i = 0; _i < 2; ++_i) \
;         __builtin_amdgcn_global_load_lds((const unsigned*)((const char*)(gbase) + (voff)[_i]), (PG8_LAS unsigned*)(lds + (bufoff) + ldsw + _i * 8192), 16, 0, 0); } while (0)
; #define PG8_LDA(dst, b, h) do { _Pragma("unroll") for (int m = 0; m < 4; ++m) _Pragma("unroll") for (int k = 0; k < 2; ++k) dst[m][k] = *(const PG8_LAS bf16x8*)(lds + PG8_SA(b, h) + aoff + m * 2048 + k * 1024); } while (0)
; #define PG8_MMA(ai, bj, At, Bt) do { __builtin_amdgcn_s_setprio(1); _Pragma("unroll") for (int m = 0; m < 4; ++m) _Pragma("unroll") for (int n = 0; n < 2; ++n) _Pragma("unroll") for (int k = 0; k < 2; ++k) \
;         acc[ai][bj][m][n] = __builtin_amdgcn_mfma_f32_16x16x32_bf16(Bt[n][k], At[m][k], acc[ai][bj][m][n], 0, 0, 0); __builtin_amdgcn_s_setprio(0); } while (0)
; #define PG8_WAIT_V(n) asm volatile("s_waitcnt vmcnt(" #n ")" ::: "memory")
; #define PG8_WAIT_L(n) asm volatile("s_waitcnt lgkmcnt(" #n ")" ::: "memory")
; #define PG8_BAR __builtin_amdgcn_s_barrier()
; #define PG8_SCHED __builtin_amdgcn_sched_barrier(0)
; template <class Epi, class Sched, bool ALIGN_EPI = false, bool SP2 = false>
; __device__ __forceinline__ void gemm_phase(PG8_LAS unsigned char* lds, const Gemm g, const Sched& S, const Epi& E) {
;     ...
;         for (int t = 0; t < nt; t += 2) {
;             const bool last = (t == nt - 2);
;     ...
;             PG8_LDA(At, 1, 1); PG8_STAGE(PG8_SB(1, 0), b3, voffB); PG8_STAGE(PG8_SB(1, 1), b3 + hstep, voffB); PG8_STAGE(PG8_SA(1, 0), a3, voffA);
;             PG8_WAIT_V(8); PG8_WAIT_L(0); PG8_BAR; PG8_MMA(1, 0, At, B0); PG8_MMA(1, 1, At, B1); PG8_BAR; PG8_SCHED;
	s_add_i32 s80, s84, s34
	v_lshl_add_u64 v[174:175], v[174:175], 0, s[38:39]
	s_mov_b32 m0, s80
	ds_read_b128 v[200:203], v180 offset:49152
	ds_read_b128 v[204:207], v180 offset:50176
	ds_read_b128 v[208:211], v180 offset:51200
	ds_read_b128 v[212:215], v180 offset:52224
	ds_read_b128 v[216:219], v180 offset:53248
	ds_read_b128 v[220:223], v180 offset:54272
	ds_read_b128 v[224:227], v180 offset:55296
	ds_read_b128 v[228:231], v180 offset:56320
	global_load_lds_dwordx4 v[174:175], off
	s_add_i32 m0, s80, 0x2000
	s_add_u32 s78, s78, 0x40080
	v_lshl_add_u64 v[174:175], v[186:187], 0, s[38:39]
	s_addc_u32 s79, s79, 0
	s_add_i32 s80, s85, s34
	global_load_lds_dwordx4 v[174:175], off
	s_mov_b32 m0, s80
	s_nop 0
	global_load_lds_dwordx4 v152, s[78:79]
	s_add_i32 m0, s80, 0x2000
	s_nop 0
	global_load_lds_dwordx4 v156, s[78:79]
	v_lshl_add_u64 v[174:175], v[232:233], 0, s[38:39]
	s_mov_b32 m0, s52
	s_nop 0
	global_load_lds_dwordx4 v[174:175], off
	v_lshl_add_u64 v[174:175], v[234:235], 0, s[38:39]
	s_mov_b32 m0, s53
	s_nop 0
	global_load_lds_dwordx4 v[174:175], off
	s_waitcnt vmcnt(8)
	s_waitcnt lgkmcnt(0)
	s_barrier
	s_setprio 1
	v_mfma_f32_16x16x32_bf16 v[62:65], v[134:137], v[200:203], v[62:65]
	v_mfma_f32_16x16x32_bf16 v[30:33], v[142:145], v[200:203], v[30:33]
	v_mfma_f32_16x16x32_bf16 v[58:61], v[134:137], v[208:211], v[58:61]
	v_mfma_f32_16x16x32_bf16 v[26:29], v[142:145], v[208:211], v[26:29]
	v_mfma_f32_16x16x32_bf16 v[54:57], v[134:137], v[216:219], v[54:57]
	v_mfma_f32_16x16x32_bf16 v[22:25], v[142:145], v[216:219], v[22:25]
	v_mfma_f32_16x16x32_bf16 v[50:53], v[134:137], v[224:227], v[50:53]
	v_mfma_f32_16x16x32_bf16 v[18:21], v[142:145], v[224:227], v[18:21]
	v_mfma_f32_16x16x32_bf16 v[62:65], v[138:141], v[204:207], v[62:65]
	v_mfma_f32_16x16x32_bf16 v[30:33], v[146:149], v[204:207], v[30:33]
	v_mfma_f32_16x16x32_bf16 v[58:61], v[138:141], v[212:215], v[58:61]
	v_mfma_f32_16x16x32_bf16 v[26:29], v[146:149], v[212:215], v[26:29]
	v_mfma_f32_16x16x32_bf16 v[54:57], v[138:141], v[220:223], v[54:57]
	v_mfma_f32_16x16x32_bf16 v[22:25], v[146:149], v[220:223], v[22:25]
	v_mfma_f32_16x16x32_bf16 v[50:53], v[138:141], v[228:231], v[50:53]
	v_mfma_f32_16x16x32_bf16 v[18:21], v[146:149], v[228:231], v[18:21]
	v_mfma_f32_16x16x32_bf16 v[34:37], v[162:165], v[200:203], v[34:37]
	v_mfma_f32_16x16x32_bf16 v[2:5], v[170:173], v[200:203], v[2:5]
	v_mfma_f32_16x16x32_bf16 v[46:49], v[162:165], v[208:211], v[46:49]
	v_mfma_f32_16x16x32_bf16 v[14:17], v[170:173], v[208:211], v[14:17]
	v_mfma_f32_16x16x32_bf16 v[42:45], v[162:165], v[216:219], v[42:45]
	v_mfma_f32_16x16x32_bf16 v[10:13], v[170:173], v[216:219], v[10:13]
	v_mfma_f32_16x16x32_bf16 v[38:41], v[162:165], v[224:227], v[38:41]
	v_mfma_f32_16x16x32_bf16 v[6:9], v[170:173], v[224:227], v[6:9]
	v_mfma_f32_16x16x32_bf16 v[34:37], v[166:169], v[204:207], v[34:37]
	v_mfma_f32_16x16x32_bf16 v[2:5], v[182:185], v[204:207], v[2:5]
	v_mfma_f32_16x16x32_bf16 v[46:49], v[166:169], v[212:215], v[46:49]
	v_mfma_f32_16x16x32_bf16 v[14:17], v[182:185], v[212:215], v[14:17]
	v_mfma_f32_16x16x32_bf16 v[42:45], v[166:169], v[220:223], v[42:45]
	v_mfma_f32_16x16x32_bf16 v[10:13], v[182:185], v[220:223], v[10:13]
	v_mfma_f32_16x16x32_bf16 v[38:41], v[166:169], v[228:231], v[38:41]
	v_mfma_f32_16x16x32_bf16 v[6:9], v[182:185], v[228:231], v[6:9]
	s_setprio 0
	s_barrier
	s_add_i32 s83, s83, 2
	s_add_u32 s75, s75, 0x100
	s_addc_u32 s82, s82, 0
	s_add_u32 s76, s76, 0x100
	s_addc_u32 s77, s77, 0
	s_cmp_gt_u32 s83, 13
	s_cbranch_scc0 .LBB0_856
	s_and_b64 vcc, exec, s[58:59]
	s_cbranch_vccz .LBB0_859
	s_barrier

; #define PG8_STAGE(bufoff, gbase, voff) do { _Pragma("unroll") for (int _i = 0; _i < 2; ++_i) \
;         __builtin_amdgcn_global_load_lds((const unsigned*)((const char*)(gbase) + (voff)[_i]), (PG8_LAS unsigned*)(lds + (bufoff) + ldsw + _i * 8192), 16, 0, 0); } while (0)
; #define PG8_LDA(dst, b, h) do { _Pragma("unroll") for (int m = 0; m < 4; ++m) _Pragma("unroll") for (int k = 0; k < 2; ++k) dst[m][k] = *(const PG8_LAS bf16x8*)(lds + PG8_SA(b, h) + aoff + m * 2048 + k * 1024); } while (0)
; #define PG8_LDB(dst, b, h) do { _Pragma("unroll") for (int n = 0; n < 2; ++n) _Pragma("unroll") for (int k = 0; k < 2; ++k) dst[n][k] = *(const PG8_LAS bf16x8*)(lds + PG8_SB(b, h) + boff + n * 2048 + k * 1024); } while (0)
; #define PG8_MMA(ai, bj, At, Bt) do { __builtin_amdgcn_s_setprio(1); _Pragma("unroll") for (int m = 0; m < 4; ++m) _Pragma("unroll") for (int n = 0; n < 2; ++n) _Pragma("unroll") for (int k = 0; k < 2; ++k) \
;         acc[ai][bj][m][n] = __builtin_amdgcn_mfma_f32_16x16x32_bf16(Bt[n][k], At[m][k], acc[ai][bj][m][n], 0, 0, 0); __builtin_amdgcn_s_setprio(0); } while (0)
; #define PG8_WAIT_V(n) asm volatile("s_waitcnt vmcnt(" #n ")" ::: "memory")
; #define PG8_WAIT_L(n) asm volatile("s_waitcnt lgkmcnt(" #n ")" ::: "memory")
; template <class Epi, class Sched, bool ALIGN_EPI = false, bool SP2 = false>
; __device__ __forceinline__ void gemm_phase(PG8_LAS unsigned char* lds, const Gemm g, const Sched& S, const Epi& E) {
;     ...
;             const bool last = (t == nt - 2);
;             const char* a1 = cA + (size_t)(t + 1) * kstep;
;             const char* a2 = last ? nA : cA + (size_t)(t + 2) * kstep; const char* b2 = last ? nB : cB + (size_t)(t + 2) * kstep;
;             const char* a3 = a2 + kstep; const char* b3 = b2 + kstep;
;             if (last && has_next) S.a_ready(nxt);
;             if constexpr (SP2) {
;             PG8_LDB(B0, 0, 0); PG8_LDB(B1, 0, 1); PG8_SCHED; PG8_LDA(At, 0, 0); PG8_STAGE(PG8_SA(1, 1), a1 + hstep, voffA);
;             PG8_WAIT_V(8); PG8_WAIT_L(0); PG8_BAR; PG8_MMA(0, 0, At, B0); PG8_MMA(0, 1, At, B1); PG8_BAR; PG8_SCHED;
;             PG8_LDA(At, 0, 1); PG8_STAGE(PG8_SB(0, 0), b2, voffB); PG8_STAGE(PG8_SB(0, 1), b2 + hstep, voffB); PG8_STAGE(PG8_SA(0, 0), a2, voffA);
;             PG8_WAIT_V(8); PG8_WAIT_L(0); PG8_BAR; PG8_MMA(1, 0, At, B0); PG8_MMA(1, 1, At, B1); PG8_BAR; PG8_SCHED;
.LBB0_1035:
	s_add_u32 s24, s20, 0x100
	s_addc_u32 s25, s21, 0
	s_add_i32 s64, 0, 0x10000
	s_cmp_eq_u32 s63, 44
	s_cselect_b32 s59, s7, s25
	s_cselect_b32 s58, s6, s24
	v_add_u32_e32 v146, s64, v148
	s_cselect_b32 s27, s19, s62
	s_cselect_b32 s26, s18, s61
	s_add_i32 s65, 0, 0x14000
	ds_read_b128 v[142:145], v146
	ds_read_b128 v[152:155], v146 offset:1024
	ds_read_b128 v[156:159], v146 offset:2048
	ds_read_b128 v[160:163], v146 offset:3072
	v_add_u32_e32 v146, s65, v148
	ds_read_b128 v[164:167], v146
	ds_read_b128 v[168:171], v146 offset:1024
	ds_read_b128 v[172:175], v146 offset:2048
	ds_read_b128 v[180:183], v146 offset:3072
	s_add_i32 m0, s37, 0xc000
	ds_read_b128 v[184:187], v150
	ds_read_b128 v[200:203], v150 offset:1024
	ds_read_b128 v[204:207], v150 offset:2048
	ds_read_b128 v[208:211], v150 offset:3072
	ds_read_b128 v[212:215], v150 offset:4096
	ds_read_b128 v[216:219], v150 offset:5120
	ds_read_b128 v[220:223], v150 offset:6144
	ds_read_b128 v[224:227], v150 offset:7168
	global_load_lds_dwordx4 v140, s[20:21]
	s_add_i32 m0, s37, 0xe000
	s_nop 0
	global_load_lds_dwordx4 v138, s[20:21]
	s_waitcnt vmcnt(8)
	s_waitcnt lgkmcnt(0)
	s_barrier
	s_setprio 1
	v_mfma_f32_16x16x32_bf16 v[130:133], v[142:145], v[184:187], v[130:133]
	v_mfma_f32_16x16x32_bf16 v[126:129], v[156:159], v[184:187], v[126:129]
	v_mfma_f32_16x16x32_bf16 v[118:121], v[142:145], v[204:207], v[118:121]
	v_mfma_f32_16x16x32_bf16 v[110:113], v[156:159], v[204:207], v[110:113]
	v_mfma_f32_16x16x32_bf16 v[102:105], v[142:145], v[212:215], v[102:105]
	v_mfma_f32_16x16x32_bf16 v[94:97], v[156:159], v[212:215], v[94:97]
	v_mfma_f32_16x16x32_bf16 v[86:89], v[142:145], v[220:223], v[86:89]
	v_mfma_f32_16x16x32_bf16 v[74:77], v[156:159], v[220:223], v[74:77]
	v_mfma_f32_16x16x32_bf16 v[130:133], v[152:155], v[200:203], v[130:133]
	v_mfma_f32_16x16x32_bf16 v[126:129], v[160:163], v[200:203], v[126:129]
	v_mfma_f32_16x16x32_bf16 v[118:121], v[152:155], v[208:211], v[118:121]
	v_mfma_f32_16x16x32_bf16 v[110:113], v[160:163], v[208:211], v[110:113]
	v_mfma_f32_16x16x32_bf16 v[102:105], v[152:155], v[216:219], v[102:105]
	v_mfma_f32_16x16x32_bf16 v[94:97], v[160:163], v[216:219], v[94:97]
	v_mfma_f32_16x16x32_bf16 v[86:89], v[152:155], v[224:227], v[86:89]
	v_mfma_f32_16x16x32_bf16 v[74:77], v[160:163], v[224:227], v[74:77]
	v_mfma_f32_16x16x32_bf16 v[122:125], v[164:167], v[184:187], v[122:125]
	v_mfma_f32_16x16x32_bf16 v[114:117], v[172:175], v[184:187], v[114:117]
	v_mfma_f32_16x16x32_bf16 v[106:109], v[164:167], v[204:207], v[106:109]
	v_mfma_f32_16x16x32_bf16 v[98:101], v[172:175], v[204:207], v[98:101]
	v_mfma_f32_16x16x32_bf16 v[90:93], v[164:167], v[212:215], v[90:93]
	v_mfma_f32_16x16x32_bf16 v[78:81], v[172:175], v[212:215], v[78:81]
	v_mfma_f32_16x16x32_bf16 v[70:73], v[164:167], v[220:223], v[70:73]
	v_mfma_f32_16x16x32_bf16 v[66:69], v[172:175], v[220:223], v[66:69]
	v_mfma_f32_16x16x32_bf16 v[122:125], v[168:171], v[200:203], v[122:125]
	v_mfma_f32_16x16x32_bf16 v[114:117], v[180:183], v[200:203], v[114:117]
	v_mfma_f32_16x16x32_bf16 v[106:109], v[168:171], v[208:211], v[106:109]
	v_mfma_f32_16x16x32_bf16 v[98:101], v[180:183], v[208:211], v[98:101]
	v_mfma_f32_16x16x32_bf16 v[90:93], v[168:171], v[216:219], v[90:93]
	v_mfma_f32_16x16x32_bf16 v[78:81], v[180:183], v[216:219], v[78:81]
	v_mfma_f32_16x16x32_bf16 v[70:73], v[168:171], v[224:227], v[70:73]
	v_mfma_f32_16x16x32_bf16 v[66:69], v[180:183], v[224:227], v[66:69]
	s_setprio 0
	s_barrier
	s_add_i32 s20, s64, s28
	v_lshl_add_u64 v[146:147], s[26:27], 0, v[136:137]
	s_mov_b32 m0, s20
	ds_read_b128 v[184:187], v150 offset:16384
	ds_read_b128 v[200:203], v150 offset:17408
	ds_read_b128 v[204:207], v150 offset:18432
	ds_read_b128 v[208:211], v150 offset:19456
	ds_read_b128 v[212:215], v150 offset:20480
	ds_read_b128 v[216:219], v150 offset:21504
	ds_read_b128 v[220:223], v150 offset:22528
	ds_read_b128 v[224:227], v150 offset:23552
	global_load_lds_dwordx4 v[146:147], off
	s_add_i32 m0, s20, 0x2000
	s_add_u32 s20, s26, 0xc0000
	v_lshl_add_u64 v[176:177], s[26:27], 0, v[134:135]
	s_addc_u32 s21, s27, 0
	s_add_i32 s64, s65, s28
	global_load_lds_dwordx4 v[176:177], off
	s_mov_b32 m0, s64
	v_lshl_add_u64 v[230:231], s[58:59], 0, v[134:135]
	global_load_lds_dwordx4 v136, s[20:21]
	s_add_i32 m0, s64, 0x2000
	s_nop 0
	global_load_lds_dwordx4 v134, s[20:21]
	v_lshl_add_u64 v[228:229], s[58:59], 0, v[136:137]
	s_mov_b32 m0, s37
	s_nop 0
	global_load_lds_dwordx4 v[228:229], off
	s_mov_b32 m0, s40
	s_nop 0
	global_load_lds_dwordx4 v[230:231], off
	s_waitcnt vmcnt(8)
	s_waitcnt lgkmcnt(0)
	s_barrier
; #define PG8_STAGE(bufoff, gbase, voff) do { _Pragma("unroll") for (int _i = 0; _i < 2; ++_i) \
;         __builtin_amdgcn_global_load_lds((const unsigned*)((const char*)(gbase) + (voff)[_i]), (PG8_LAS unsigned*)(lds + (bufoff) + ldsw + _i * 8192), 16, 0, 0); } while (0)
; #define PG8_LDA(dst, b, h) do { _Pragma("unroll") for (int m = 0; m < 4; ++m) _Pragma("unroll") for (int k = 0; k < 2; ++k) dst[m][k] = *(const PG8_LAS bf16x8*)(lds + PG8_SA(b, h) + aoff + m * 2048 + k * 1024); } while (0)
; #define PG8_LDB(dst, b, h) do { _Pragma("unroll") for (int n = 0; n < 2; ++n) _Pragma("unroll") for (int k = 0; k < 2; ++k) dst[n][k] = *(const PG8_LAS bf16x8*)(lds + PG8_SB(b, h) + boff + n * 2048 + k * 1024); } while (0)
; #define PG8_MMA(ai, bj, At, Bt) do { __builtin_amdgcn_s_setprio(1); _Pragma("unroll") for (int m = 0; m < 4; ++m) _Pragma("unroll") for (int n = 0; n < 2; ++n) _Pragma("unroll") for (int k = 0; k < 2; ++k) \
;         acc[ai][bj][m][n] = __builtin_amdgcn_mfma_f32_16x16x32_bf16(Bt[n][k], At[m][k], acc[ai][bj][m][n], 0, 0, 0); __builtin_amdgcn_s_setprio(0); } while (0)
; #define PG8_WAIT_V(n) asm volatile("s_waitcnt vmcnt(" #n ")" ::: "memory")
; #define PG8_WAIT_L(n) asm volatile("s_waitcnt lgkmcnt(" #n ")" ::: "memory")
; #define PG8_BAR __builtin_amdgcn_s_barrier()
; #define PG8_SCHED __builtin_amdgcn_sched_barrier(0)
; template <class Epi, class Sched, bool ALIGN_EPI = false, bool SP2 = false>
; __device__ __forceinline__ void gemm_phase(PG8_LAS unsigned char* lds, const Gemm g, const Sched& S, const Epi& E) {
;     ...
;             PG8_WAIT_V(8); PG8_WAIT_L(0); PG8_BAR; PG8_MMA(1, 0, At, B0); PG8_MMA(1, 1, At, B1); PG8_BAR; PG8_SCHED;
;             PG8_LDB(B0, 1, 0); PG8_LDB(B1, 1, 1); PG8_SCHED; PG8_LDA(At, 1, 0); PG8_STAGE(PG8_SA(0, 1), a2 + hstep, voffA);
;             PG8_WAIT_V(8); PG8_WAIT_L(0); PG8_BAR; PG8_MMA(0, 0, At, B0); PG8_MMA(0, 1, At, B1); PG8_BAR; PG8_SCHED;
	s_setprio 1
	v_mfma_f32_16x16x32_bf16 v[62:65], v[142:145], v[184:187], v[62:65]
	v_mfma_f32_16x16x32_bf16 v[58:61], v[156:159], v[184:187], v[58:61]
	v_mfma_f32_16x16x32_bf16 v[50:53], v[142:145], v[204:207], v[50:53]
	v_mfma_f32_16x16x32_bf16 v[42:45], v[156:159], v[204:207], v[42:45]
	v_mfma_f32_16x16x32_bf16 v[34:37], v[142:145], v[212:215], v[34:37]
	v_mfma_f32_16x16x32_bf16 v[26:29], v[156:159], v[212:215], v[26:29]
	v_mfma_f32_16x16x32_bf16 v[18:21], v[142:145], v[220:223], v[18:21]
	v_mfma_f32_16x16x32_bf16 v[10:13], v[156:159], v[220:223], v[10:13]
	v_mfma_f32_16x16x32_bf16 v[62:65], v[152:155], v[200:203], v[62:65]
	v_mfma_f32_16x16x32_bf16 v[58:61], v[160:163], v[200:203], v[58:61]
	v_mfma_f32_16x16x32_bf16 v[50:53], v[152:155], v[208:211], v[50:53]
	v_mfma_f32_16x16x32_bf16 v[42:45], v[160:163], v[208:211], v[42:45]
	v_mfma_f32_16x16x32_bf16 v[34:37], v[152:155], v[216:219], v[34:37]
	v_mfma_f32_16x16x32_bf16 v[26:29], v[160:163], v[216:219], v[26:29]
	v_mfma_f32_16x16x32_bf16 v[18:21], v[152:155], v[224:227], v[18:21]
	v_mfma_f32_16x16x32_bf16 v[10:13], v[160:163], v[224:227], v[10:13]
	v_mfma_f32_16x16x32_bf16 v[54:57], v[164:167], v[184:187], v[54:57]
	v_mfma_f32_16x16x32_bf16 v[46:49], v[172:175], v[184:187], v[46:49]
	v_mfma_f32_16x16x32_bf16 v[38:41], v[164:167], v[204:207], v[38:41]
	v_mfma_f32_16x16x32_bf16 v[30:33], v[172:175], v[204:207], v[30:33]
	v_mfma_f32_16x16x32_bf16 v[22:25], v[164:167], v[212:215], v[22:25]
	v_mfma_f32_16x16x32_bf16 v[14:17], v[172:175], v[212:215], v[14:17]
	v_mfma_f32_16x16x32_bf16 v[6:9], v[164:167], v[220:223], v[6:9]
	v_mfma_f32_16x16x32_bf16 v[2:5], v[172:175], v[220:223], v[2:5]
	v_mfma_f32_16x16x32_bf16 v[54:57], v[168:171], v[200:203], v[54:57]
	v_mfma_f32_16x16x32_bf16 v[46:49], v[180:183], v[200:203], v[46:49]
	v_mfma_f32_16x16x32_bf16 v[38:41], v[168:171], v[208:211], v[38:41]
	v_mfma_f32_16x16x32_bf16 v[30:33], v[180:183], v[208:211], v[30:33]
	v_mfma_f32_16x16x32_bf16 v[22:25], v[168:171], v[216:219], v[22:25]
	v_mfma_f32_16x16x32_bf16 v[14:17], v[180:183], v[216:219], v[14:17]
	v_mfma_f32_16x16x32_bf16 v[6:9], v[168:171], v[224:227], v[6:9]
	v_mfma_f32_16x16x32_bf16 v[2:5], v[180:183], v[224:227], v[2:5]
	s_setprio 0
	s_barrier
	s_add_i32 s64, 0, 0x18000
	v_add_u32_e32 v151, s64, v148
	s_add_i32 s65, 0, 0x1c000
	ds_read_b128 v[142:145], v151
	ds_read_b128 v[152:155], v151 offset:1024
	ds_read_b128 v[156:159], v151 offset:2048
	ds_read_b128 v[160:163], v151 offset:3072
	v_add_u32_e32 v151, s65, v148
	ds_read_b128 v[164:167], v151
	ds_read_b128 v[168:171], v151 offset:1024
	ds_read_b128 v[172:175], v151 offset:2048
	ds_read_b128 v[180:183], v151 offset:3072
	s_add_u32 s20, s58, 0xc0000
	s_addc_u32 s21, s59, 0
	s_mov_b32 m0, s41
	ds_read_b128 v[184:187], v150 offset:32768
	ds_read_b128 v[200:203], v150 offset:33792
	ds_read_b128 v[204:207], v150 offset:34816
	ds_read_b128 v[208:211], v150 offset:35840
	ds_read_b128 v[212:215], v150 offset:36864
	ds_read_b128 v[216:219], v150 offset:37888
	ds_read_b128 v[220:223], v150 offset:38912
	ds_read_b128 v[224:227], v150 offset:39936
	global_load_lds_dwordx4 v136, s[20:21]
	s_mov_b32 m0, s42
	s_nop 0
	global_load_lds_dwordx4 v134, s[20:21]
	s_waitcnt vmcnt(8)
	s_waitcnt lgkmcnt(0)
	s_barrier
	s_setprio 1
	v_mfma_f32_16x16x32_bf16 v[130:133], v[142:145], v[184:187], v[130:133]
	v_mfma_f32_16x16x32_bf16 v[126:129], v[156:159], v[184:187], v[126:129]
	v_mfma_f32_16x16x32_bf16 v[118:121], v[142:145], v[204:207], v[118:121]
	v_mfma_f32_16x16x32_bf16 v[110:113], v[156:159], v[204:207], v[110:113]
	v_mfma_f32_16x16x32_bf16 v[102:105], v[142:145], v[212:215], v[102:105]
	v_mfma_f32_16x16x32_bf16 v[94:97], v[156:159], v[212:215], v[94:97]
	v_mfma_f32_16x16x32_bf16 v[86:89], v[142:145], v[220:223], v[86:89]
	v_mfma_f32_16x16x32_bf16 v[74:77], v[156:159], v[220:223], v[74:77]
	v_mfma_f32_16x16x32_bf16 v[130:133], v[152:155], v[200:203], v[130:133]
	v_mfma_f32_16x16x32_bf16 v[126:129], v[160:163], v[200:203], v[126:129]
	v_mfma_f32_16x16x32_bf16 v[118:121], v[152:155], v[208:211], v[118:121]
	v_mfma_f32_16x16x32_bf16 v[110:113], v[160:163], v[208:211], v[110:113]
	v_mfma_f32_16x16x32_bf16 v[102:105], v[152:155], v[216:219], v[102:105]
	v_mfma_f32_16x16x32_bf16 v[94:97], v[160:163], v[216:219], v[94:97]
	v_mfma_f32_16x16x32_bf16 v[86:89], v[152:155], v[224:227], v[86:89]
	v_mfma_f32_16x16x32_bf16 v[74:77], v[160:163], v[224:227], v[74:77]
	v_mfma_f32_16x16x32_bf16 v[122:125], v[164:167], v[184:187], v[122:125]
	v_mfma_f32_16x16x32_bf16 v[114:117], v[172:175], v[184:187], v[114:117]
	v_mfma_f32_16x16x32_bf16 v[106:109], v[164:167], v[204:207], v[106:109]
	v_mfma_f32_16x16x32_bf16 v[98:101], v[172:175], v[204:207], v[98:101]
	v_mfma_f32_16x16x32_bf16 v[90:93], v[164:167], v[212:215], v[90:93]
	v_mfma_f32_16x16x32_bf16 v[78:81], v[172:175], v[212:215], v[78:81]
	v_mfma_f32_16x16x32_bf16 v[70:73], v[164:167], v[220:223], v[70:73]
	v_mfma_f32_16x16x32_bf16 v[66:69], v[172:175], v[220:223], v[66:69]
	v_mfma_f32_16x16x32_bf16 v[122:125], v[168:171], v[200:203], v[122:125]
	v_mfma_f32_16x16x32_bf16 v[114:117], v[180:183], v[200:203], v[114:117]
	v_mfma_f32_16x16x32_bf16 v[106:109], v[168:171], v[208:211], v[106:109]
	v_mfma_f32_16x16x32_bf16 v[98:101], v[180:183], v[208:211], v[98:101]
	v_mfma_f32_16x16x32_bf16 v[90:93], v[168:171], v[216:219], v[90:93]
	v_mfma_f32_16x16x32_bf16 v[78:81], v[180:183], v[216:219], v[78:81]
	v_mfma_f32_16x16x32_bf16 v[70:73], v[168:171], v[224:227], v[70:73]
	v_mfma_f32_16x16x32_bf16 v[66:69], v[180:183], v[224:227], v[66:69]
	s_setprio 0
	s_barrier
; #define PG8_STAGE(bufoff, gbase, voff) do { _Pragma("unroll") for (int _i = 0; _i < 2; ++_i) \
;         __builtin_amdgcn_global_load_lds((const unsigned*)((const char*)(gbase) + (voff)[_i]), (PG8_LAS unsigned*)(lds + (bufoff) + ldsw + _i * 8192), 16, 0, 0); } while (0)
; #define PG8_LDA(dst, b, h) do { _Pragma("unroll") for (int m = 0; m < 4; ++m) _Pragma("unroll") for (int k = 0; k < 2; ++k) dst[m][k] = *(const PG8_LAS bf16x8*)(lds + PG8_SA(b, h) + aoff + m * 2048 + k * 1024); } while (0)
; #define PG8_MMA(ai, bj, At, Bt) do { __builtin_amdgcn_s_setprio(1); _Pragma("unroll") for (int m = 0; m < 4; ++m) _Pragma("unroll") for (int n = 0; n < 2; ++n) _Pragma("unroll") for (int k = 0; k < 2; ++k) \
;         acc[ai][bj][m][n] = __builtin_amdgcn_mfma_f32_16x16x32_bf16(Bt[n][k], At[m][k], acc[ai][bj][m][n], 0, 0, 0); __builtin_amdgcn_s_setprio(0); } while (0)
; #define PG8_WAIT_V(n) asm volatile("s_waitcnt vmcnt(" #n ")" ::: "memory")
; #define PG8_WAIT_L(n) asm volatile("s_waitcnt lgkmcnt(" #n ")" ::: "memory")
; #define PG8_BAR __builtin_amdgcn_s_barrier()
; #define PG8_SCHED __builtin_amdgcn_sched_barrier(0)
; template <class Epi, class Sched, bool ALIGN_EPI = false, bool SP2 = false>
; __device__ __forceinline__ void gemm_phase(PG8_LAS unsigned char* lds, const Gemm g, const Sched& S, const Epi& E) {
;     ...
;         for (int t = 0; t < nt; t += 2) {
;             const bool last = (t == nt - 2);
;     ...
;             PG8_LDA(At, 1, 1); PG8_STAGE(PG8_SB(1, 0), b3, voffB); PG8_STAGE(PG8_SB(1, 1), b3 + hstep, voffB); PG8_STAGE(PG8_SA(1, 0), a3, voffA);
;             PG8_WAIT_V(8); PG8_WAIT_L(0); PG8_BAR; PG8_MMA(1, 0, At, B0); PG8_MMA(1, 1, At, B1); PG8_BAR; PG8_SCHED;
	s_add_i32 s20, s64, s28
	v_lshl_add_u64 v[146:147], v[146:147], 0, s[38:39]
	s_mov_b32 m0, s20
	ds_read_b128 v[184:187], v150 offset:49152
	ds_read_b128 v[200:203], v150 offset:50176
	ds_read_b128 v[204:207], v150 offset:51200
	ds_read_b128 v[208:211], v150 offset:52224
	ds_read_b128 v[212:215], v150 offset:53248
	ds_read_b128 v[216:219], v150 offset:54272
	ds_read_b128 v[220:223], v150 offset:55296
	ds_read_b128 v[224:227], v150 offset:56320
	global_load_lds_dwordx4 v[146:147], off
	s_add_i32 m0, s20, 0x2000
	s_add_u32 s20, s26, 0xc0080
	v_lshl_add_u64 v[146:147], v[176:177], 0, s[38:39]
	s_addc_u32 s21, s27, 0
	s_add_i32 s26, s65, s28
	global_load_lds_dwordx4 v[146:147], off
	s_mov_b32 m0, s26
	s_nop 0
	global_load_lds_dwordx4 v136, s[20:21]
	s_add_i32 m0, s26, 0x2000
	s_nop 0
	global_load_lds_dwordx4 v134, s[20:21]
	v_lshl_add_u64 v[146:147], v[228:229], 0, s[38:39]
	s_mov_b32 m0, s49
	s_nop 0
	global_load_lds_dwordx4 v[146:147], off
	v_lshl_add_u64 v[146:147], v[230:231], 0, s[38:39]
	s_mov_b32 m0, s52
	s_nop 0
	global_load_lds_dwordx4 v[146:147], off
	s_waitcnt vmcnt(8)
	s_waitcnt lgkmcnt(0)
	s_barrier
	s_setprio 1
	v_mfma_f32_16x16x32_bf16 v[62:65], v[142:145], v[184:187], v[62:65]
	v_mfma_f32_16x16x32_bf16 v[58:61], v[156:159], v[184:187], v[58:61]
	v_mfma_f32_16x16x32_bf16 v[50:53], v[142:145], v[204:207], v[50:53]
	v_mfma_f32_16x16x32_bf16 v[42:45], v[156:159], v[204:207], v[42:45]
	v_mfma_f32_16x16x32_bf16 v[34:37], v[142:145], v[212:215], v[34:37]
	v_mfma_f32_16x16x32_bf16 v[26:29], v[156:159], v[212:215], v[26:29]
	v_mfma_f32_16x16x32_bf16 v[18:21], v[142:145], v[220:223], v[18:21]
	v_mfma_f32_16x16x32_bf16 v[10:13], v[156:159], v[220:223], v[10:13]
	v_mfma_f32_16x16x32_bf16 v[62:65], v[152:155], v[200:203], v[62:65]
	v_mfma_f32_16x16x32_bf16 v[58:61], v[160:163], v[200:203], v[58:61]
	v_mfma_f32_16x16x32_bf16 v[50:53], v[152:155], v[208:211], v[50:53]
	v_mfma_f32_16x16x32_bf16 v[42:45], v[160:163], v[208:211], v[42:45]
	v_mfma_f32_16x16x32_bf16 v[34:37], v[152:155], v[216:219], v[34:37]
	v_mfma_f32_16x16x32_bf16 v[26:29], v[160:163], v[216:219], v[26:29]
	v_mfma_f32_16x16x32_bf16 v[18:21], v[152:155], v[224:227], v[18:21]
	v_mfma_f32_16x16x32_bf16 v[10:13], v[160:163], v[224:227], v[10:13]
	v_mfma_f32_16x16x32_bf16 v[54:57], v[164:167], v[184:187], v[54:57]
	v_mfma_f32_16x16x32_bf16 v[46:49], v[172:175], v[184:187], v[46:49]
	v_mfma_f32_16x16x32_bf16 v[38:41], v[164:167], v[204:207], v[38:41]
	v_mfma_f32_16x16x32_bf16 v[30:33], v[172:175], v[204:207], v[30:33]
	v_mfma_f32_16x16x32_bf16 v[22:25], v[164:167], v[212:215], v[22:25]
	v_mfma_f32_16x16x32_bf16 v[14:17], v[172:175], v[212:215], v[14:17]
	v_mfma_f32_16x16x32_bf16 v[6:9], v[164:167], v[220:223], v[6:9]
	v_mfma_f32_16x16x32_bf16 v[2:5], v[172:175], v[220:223], v[2:5]
	v_mfma_f32_16x16x32_bf16 v[54:57], v[168:171], v[200:203], v[54:57]
	v_mfma_f32_16x16x32_bf16 v[46:49], v[180:183], v[200:203], v[46:49]
	v_mfma_f32_16x16x32_bf16 v[38:41], v[168:171], v[208:211], v[38:41]
	v_mfma_f32_16x16x32_bf16 v[30:33], v[180:183], v[208:211], v[30:33]
	v_mfma_f32_16x16x32_bf16 v[22:25], v[168:171], v[216:219], v[22:25]
	v_mfma_f32_16x16x32_bf16 v[14:17], v[180:183], v[216:219], v[14:17]
	v_mfma_f32_16x16x32_bf16 v[6:9], v[168:171], v[224:227], v[6:9]
	v_mfma_f32_16x16x32_bf16 v[2:5], v[180:183], v[224:227], v[2:5]
	s_setprio 0
	s_barrier
	s_add_i32 s63, s63, 2
	s_add_u32 s61, s61, 0x100
	s_addc_u32 s62, s62, 0
	s_cmp_gt_u32 s63, 45
	s_mov_b64 s[20:21], s[24:25]
	s_cbranch_scc0 .LBB0_1035
	s_and_b64 vcc, exec, s[16:17]
	s_cbranch_vccz .LBB0_1038
	s_barrier
